# skinny GEMM row split (2 WGs per slice) + 4-chunk prefetch; sample attention item pairing
# speedup vs baseline: 1.0069x; 1.0069x over previous
.LBB0_129:
	s_lshl_b32 s37, s33, 5
	v_or_b32_e32 v2, s37, v76
	v_ashrrev_i32_e32 v3, 31, v2
	v_lshlrev_b64 v[2:3], 12, v[2:3]
	v_lshl_add_u64 v[18:19], v[24:25], 0, v[2:3]
	s_mov_b64 s[0:1], -1
	s_mov_b32 s18, s19
	v_mov_b32_e32 v2, 0
	v_mov_b32_e32 v3, v21
	v_mov_b32_e32 v4, v21
	v_mov_b32_e32 v5, v21
	v_mov_b32_e32 v6, v21
	v_mov_b32_e32 v7, v21
	v_mov_b32_e32 v8, v21
	v_mov_b32_e32 v9, v21
	v_mov_b32_e32 v10, v21
	v_mov_b32_e32 v11, v21
	v_mov_b32_e32 v12, v21
	v_mov_b32_e32 v13, v21
	v_mov_b32_e32 v14, v21
	v_mov_b32_e32 v15, v21
	v_mov_b32_e32 v16, v21
	v_mov_b32_e32 v17, v21
	v_readfirstlane_b32 s66, v22
	v_readfirstlane_b32 s67, v23
	v_readfirstlane_b32 s68, v18
	v_readfirstlane_b32 s69, v19
	v_readfirstlane_b32 s70, v0
	v_mbcnt_lo_u32_b32 v220, -1, 0
	v_mbcnt_hi_u32_b32 v220, -1, v220
	s_lshr_b32 s70, s70, 6
	s_mul_i32 s70, s70, 9216
	s_add_i32 s70, s70, 36864
	v_lshrrev_b32_e32 v221, 3, v220
	v_and_b32_e32 v222, 7, v220
	v_lshlrev_b32_e32 v224, 12, v221
	v_lshl_add_u32 v224, v222, 4, v224
	v_mul_u32_u24_e32 v225, 144, v221
	v_lshl_add_u32 v225, v222, 4, v225
	v_add_u32_e32 v225, s70, v225
	v_and_b32_e32 v221, 31, v220
	v_lshrrev_b32_e32 v222, 5, v220
	v_mul_u32_u24_e32 v226, 144, v221
	v_lshl_add_u32 v226, v222, 4, v226
	v_add_u32_e32 v226, s70, v226
	s_add_u32 s72, s66, 0
	s_addc_u32 s73, s67, 0
	s_add_u32 s74, s68, 0
	s_addc_u32 s75, s69, 0
	global_load_dwordx4 v[106:109], v224, s[72:73]
	global_load_dwordx4 v[122:125], v224, s[74:75]
	s_add_u32 s72, s66, 32768
	s_addc_u32 s73, s67, 0
	s_add_u32 s74, s68, 32768
	s_addc_u32 s75, s69, 0
	global_load_dwordx4 v[110:113], v224, s[72:73]
	global_load_dwordx4 v[126:129], v224, s[74:75]
	s_add_u32 s72, s66, 65536
	s_addc_u32 s73, s67, 0
	s_add_u32 s74, s68, 65536
	s_addc_u32 s75, s69, 0
	global_load_dwordx4 v[114:117], v224, s[72:73]
	global_load_dwordx4 v[130:133], v224, s[74:75]
	s_add_u32 s72, s66, 98304
	s_addc_u32 s73, s67, 0
	s_add_u32 s74, s68, 98304
	s_addc_u32 s75, s69, 0
	global_load_dwordx4 v[118:121], v224, s[72:73]
	global_load_dwordx4 v[134:137], v224, s[74:75]
	s_add_u32 s72, s66, 128
	s_addc_u32 s73, s67, 0
	s_add_u32 s74, s68, 128
	s_addc_u32 s75, s69, 0
	global_load_dwordx4 v[138:141], v224, s[72:73]
	global_load_dwordx4 v[172:175], v224, s[74:75]
	s_add_u32 s72, s66, 32896
	s_addc_u32 s73, s67, 0
	s_add_u32 s74, s68, 32896
	s_addc_u32 s75, s69, 0
	global_load_dwordx4 v[142:145], v224, s[72:73]
	global_load_dwordx4 v[176:179], v224, s[74:75]
	s_add_u32 s72, s66, 65664
	s_addc_u32 s73, s67, 0
	s_add_u32 s74, s68, 65664
	s_addc_u32 s75, s69, 0
	global_load_dwordx4 v[146:149], v224, s[72:73]
	global_load_dwordx4 v[180:183], v224, s[74:75]
	s_add_u32 s72, s66, 98432
	s_addc_u32 s73, s67, 0
	s_add_u32 s74, s68, 98432
	s_addc_u32 s75, s69, 0
	global_load_dwordx4 v[168:171], v224, s[72:73]
	global_load_dwordx4 v[184:187], v224, s[74:75]
	s_add_u32 s72, s66, 256
	s_addc_u32 s73, s67, 0
	s_add_u32 s74, s68, 256
	s_addc_u32 s75, s69, 0
	global_load_dwordx4 v[188:191], v224, s[72:73]
	global_load_dwordx4 v[204:207], v224, s[74:75]
	s_add_u32 s72, s66, 33024
	s_addc_u32 s73, s67, 0
	s_add_u32 s74, s68, 33024
	s_addc_u32 s75, s69, 0
	global_load_dwordx4 v[192:195], v224, s[72:73]
	global_load_dwordx4 v[208:211], v224, s[74:75]
	s_add_u32 s72, s66, 65792
	s_addc_u32 s73, s67, 0
	s_add_u32 s74, s68, 65792
	s_addc_u32 s75, s69, 0
	global_load_dwordx4 v[196:199], v224, s[72:73]
	global_load_dwordx4 v[212:215], v224, s[74:75]
	s_add_u32 s72, s66, 98560
	s_addc_u32 s73, s67, 0
	s_add_u32 s74, s68, 98560
	s_addc_u32 s75, s69, 0
	global_load_dwordx4 v[200:203], v224, s[72:73]
	global_load_dwordx4 v[216:219], v224, s[74:75]
	s_add_u32 s72, s66, 384
	s_addc_u32 s73, s67, 0
	s_add_u32 s74, s68, 384
	s_addc_u32 s75, s69, 0
	global_load_dwordx4 v[228:231], v224, s[72:73]
	global_load_dwordx4 v[244:247], v224, s[74:75]
	s_add_u32 s72, s66, 33152
	s_addc_u32 s73, s67, 0
	s_add_u32 s74, s68, 33152
	s_addc_u32 s75, s69, 0
	global_load_dwordx4 v[232:235], v224, s[72:73]
	global_load_dwordx4 v[248:251], v224, s[74:75]
	s_add_u32 s72, s66, 65920
	s_addc_u32 s73, s67, 0
	s_add_u32 s74, s68, 65920
	s_addc_u32 s75, s69, 0
	global_load_dwordx4 v[236:239], v224, s[72:73]
	global_load_dwordx4 v[52:55], v224, s[74:75]
	s_add_u32 s72, s66, 98688
	s_addc_u32 s73, s67, 0
	s_add_u32 s74, s68, 98688
	s_addc_u32 s75, s69, 0
	global_load_dwordx4 v[240:243], v224, s[72:73]
	global_load_dwordx4 v[56:59], v224, s[74:75]
	s_waitcnt vmcnt(24)
	ds_write_b128 v225, v[106:109]
	ds_write_b128 v225, v[110:113] offset:1152
	ds_write_b128 v225, v[114:117] offset:2304
	ds_write_b128 v225, v[118:121] offset:3456
	ds_write_b128 v225, v[122:125] offset:4608
	ds_write_b128 v225, v[126:129] offset:5760
	ds_write_b128 v225, v[130:133] offset:6912
	ds_write_b128 v225, v[134:137] offset:8064
	s_nop 1
	s_add_u32 s72, s66, 512
	s_addc_u32 s73, s67, 0
	s_add_u32 s74, s68, 512
	s_addc_u32 s75, s69, 0
	global_load_dwordx4 v[106:109], v224, s[72:73]
	global_load_dwordx4 v[122:125], v224, s[74:75]
	s_add_u32 s72, s66, 33280
	s_addc_u32 s73, s67, 0
	s_add_u32 s74, s68, 33280
	s_addc_u32 s75, s69, 0
	global_load_dwordx4 v[110:113], v224, s[72:73]
	global_load_dwordx4 v[126:129], v224, s[74:75]
	s_add_u32 s72, s66, 66048
	s_addc_u32 s73, s67, 0
	s_add_u32 s74, s68, 66048
	s_addc_u32 s75, s69, 0
	global_load_dwordx4 v[114:117], v224, s[72:73]
	global_load_dwordx4 v[130:133], v224, s[74:75]
	s_add_u32 s72, s66, 98816
	s_addc_u32 s73, s67, 0
	s_add_u32 s74, s68, 98816
	s_addc_u32 s75, s69, 0
	global_load_dwordx4 v[118:121], v224, s[72:73]
	global_load_dwordx4 v[134:137], v224, s[74:75]
	s_waitcnt lgkmcnt(0)
	ds_read_b128 v[60:63], v226
	ds_read_b128 v[64:67], v226 offset:4608
	ds_read_b128 v[68:71], v226 offset:32
	ds_read_b128 v[80:83], v226 offset:4640
	ds_read_b128 v[88:91], v226 offset:64
	ds_read_b128 v[92:95], v226 offset:4672
	ds_read_b128 v[96:99], v226 offset:96
	ds_read_b128 v[100:103], v226 offset:4704
	s_waitcnt lgkmcnt(6)
	v_mfma_f32_32x32x16_bf16 v[2:17], v[60:63], v[64:67], v[2:17]
	s_waitcnt lgkmcnt(4)
	v_mfma_f32_32x32x16_bf16 v[2:17], v[68:71], v[80:83], v[2:17]
	s_waitcnt lgkmcnt(2)
	v_mfma_f32_32x32x16_bf16 v[2:17], v[88:91], v[92:95], v[2:17]
	s_waitcnt lgkmcnt(0)
	v_mfma_f32_32x32x16_bf16 v[2:17], v[96:99], v[100:103], v[2:17]
	s_waitcnt vmcnt(24)
	ds_write_b128 v225, v[138:141]
	ds_write_b128 v225, v[142:145] offset:1152
	ds_write_b128 v225, v[146:149] offset:2304
	ds_write_b128 v225, v[168:171] offset:3456
	ds_write_b128 v225, v[172:175] offset:4608
	ds_write_b128 v225, v[176:179] offset:5760
	ds_write_b128 v225, v[180:183] offset:6912
	ds_write_b128 v225, v[184:187] offset:8064
	s_nop 1
	s_add_u32 s72, s66, 640
	s_addc_u32 s73, s67, 0
	s_add_u32 s74, s68, 640
	s_addc_u32 s75, s69, 0
	global_load_dwordx4 v[138:141], v224, s[72:73]
	global_load_dwordx4 v[172:175], v224, s[74:75]
	s_add_u32 s72, s66, 33408
	s_addc_u32 s73, s67, 0
	s_add_u32 s74, s68, 33408
	s_addc_u32 s75, s69, 0
	global_load_dwordx4 v[142:145], v224, s[72:73]
	global_load_dwordx4 v[176:179], v224, s[74:75]
	s_add_u32 s72, s66, 66176
	s_addc_u32 s73, s67, 0
	s_add_u32 s74, s68, 66176
	s_addc_u32 s75, s69, 0
	global_load_dwordx4 v[146:149], v224, s[72:73]
	global_load_dwordx4 v[180:183], v224, s[74:75]
	s_add_u32 s72, s66, 98944
	s_addc_u32 s73, s67, 0
	s_add_u32 s74, s68, 98944
	s_addc_u32 s75, s69, 0
	global_load_dwordx4 v[168:171], v224, s[72:73]
	global_load_dwordx4 v[184:187], v224, s[74:75]
	s_waitcnt lgkmcnt(0)
	ds_read_b128 v[60:63], v226
	ds_read_b128 v[64:67], v226 offset:4608
	ds_read_b128 v[68:71], v226 offset:32
	ds_read_b128 v[80:83], v226 offset:4640
	ds_read_b128 v[88:91], v226 offset:64
	ds_read_b128 v[92:95], v226 offset:4672
	ds_read_b128 v[96:99], v226 offset:96
	ds_read_b128 v[100:103], v226 offset:4704
	s_waitcnt lgkmcnt(6)
	v_mfma_f32_32x32x16_bf16 v[2:17], v[60:63], v[64:67], v[2:17]
	s_waitcnt lgkmcnt(4)
	v_mfma_f32_32x32x16_bf16 v[2:17], v[68:71], v[80:83], v[2:17]
	s_waitcnt lgkmcnt(2)
	v_mfma_f32_32x32x16_bf16 v[2:17], v[88:91], v[92:95], v[2:17]
	s_waitcnt lgkmcnt(0)
	v_mfma_f32_32x32x16_bf16 v[2:17], v[96:99], v[100:103], v[2:17]
	s_waitcnt vmcnt(24)
	ds_write_b128 v225, v[188:191]
	ds_write_b128 v225, v[192:195] offset:1152
	ds_write_b128 v225, v[196:199] offset:2304
	ds_write_b128 v225, v[200:203] offset:3456
	ds_write_b128 v225, v[204:207] offset:4608
	ds_write_b128 v225, v[208:211] offset:5760
	ds_write_b128 v225, v[212:215] offset:6912
	ds_write_b128 v225, v[216:219] offset:8064
	s_nop 1
	s_add_u32 s72, s66, 768
	s_addc_u32 s73, s67, 0
	s_add_u32 s74, s68, 768
	s_addc_u32 s75, s69, 0
	global_load_dwordx4 v[188:191], v224, s[72:73]
	global_load_dwordx4 v[204:207], v224, s[74:75]
	s_add_u32 s72, s66, 33536
	s_addc_u32 s73, s67, 0
	s_add_u32 s74, s68, 33536
	s_addc_u32 s75, s69, 0
	global_load_dwordx4 v[192:195], v224, s[72:73]
	global_load_dwordx4 v[208:211], v224, s[74:75]
	s_add_u32 s72, s66, 66304
	s_addc_u32 s73, s67, 0
	s_add_u32 s74, s68, 66304
	s_addc_u32 s75, s69, 0
	global_load_dwordx4 v[196:199], v224, s[72:73]
	global_load_dwordx4 v[212:215], v224, s[74:75]
	s_add_u32 s72, s66, 99072
	s_addc_u32 s73, s67, 0
	s_add_u32 s74, s68, 99072
	s_addc_u32 s75, s69, 0
	global_load_dwordx4 v[200:203], v224, s[72:73]
	global_load_dwordx4 v[216:219], v224, s[74:75]
	s_waitcnt lgkmcnt(0)
	ds_read_b128 v[60:63], v226
	ds_read_b128 v[64:67], v226 offset:4608
	ds_read_b128 v[68:71], v226 offset:32
	ds_read_b128 v[80:83], v226 offset:4640
	ds_read_b128 v[88:91], v226 offset:64
	ds_read_b128 v[92:95], v226 offset:4672
	ds_read_b128 v[96:99], v226 offset:96
	ds_read_b128 v[100:103], v226 offset:4704
	s_waitcnt lgkmcnt(6)
	v_mfma_f32_32x32x16_bf16 v[2:17], v[60:63], v[64:67], v[2:17]
	s_waitcnt lgkmcnt(4)
	v_mfma_f32_32x32x16_bf16 v[2:17], v[68:71], v[80:83], v[2:17]
	s_waitcnt lgkmcnt(2)
	v_mfma_f32_32x32x16_bf16 v[2:17], v[88:91], v[92:95], v[2:17]
	s_waitcnt lgkmcnt(0)
	v_mfma_f32_32x32x16_bf16 v[2:17], v[96:99], v[100:103], v[2:17]
	s_waitcnt vmcnt(24)
	ds_write_b128 v225, v[228:231]
	ds_write_b128 v225, v[232:235] offset:1152
	ds_write_b128 v225, v[236:239] offset:2304
	ds_write_b128 v225, v[240:243] offset:3456
	ds_write_b128 v225, v[244:247] offset:4608
	ds_write_b128 v225, v[248:251] offset:5760
	ds_write_b128 v225, v[52:55] offset:6912
	ds_write_b128 v225, v[56:59] offset:8064
	s_nop 1
	s_add_u32 s72, s66, 896
	s_addc_u32 s73, s67, 0
	s_add_u32 s74, s68, 896
	s_addc_u32 s75, s69, 0
	global_load_dwordx4 v[228:231], v224, s[72:73]
	global_load_dwordx4 v[244:247], v224, s[74:75]
	s_add_u32 s72, s66, 33664
	s_addc_u32 s73, s67, 0
	s_add_u32 s74, s68, 33664
	s_addc_u32 s75, s69, 0
	global_load_dwordx4 v[232:235], v224, s[72:73]
	global_load_dwordx4 v[248:251], v224, s[74:75]
	s_add_u32 s72, s66, 66432
	s_addc_u32 s73, s67, 0
	s_add_u32 s74, s68, 66432
	s_addc_u32 s75, s69, 0
	global_load_dwordx4 v[236:239], v224, s[72:73]
	global_load_dwordx4 v[52:55], v224, s[74:75]
	s_add_u32 s72, s66, 99200
	s_addc_u32 s73, s67, 0
	s_add_u32 s74, s68, 99200
	s_addc_u32 s75, s69, 0
	global_load_dwordx4 v[240:243], v224, s[72:73]
	global_load_dwordx4 v[56:59], v224, s[74:75]
	s_waitcnt lgkmcnt(0)
	ds_read_b128 v[60:63], v226
	ds_read_b128 v[64:67], v226 offset:4608
	ds_read_b128 v[68:71], v226 offset:32
	ds_read_b128 v[80:83], v226 offset:4640
	ds_read_b128 v[88:91], v226 offset:64
	ds_read_b128 v[92:95], v226 offset:4672
	ds_read_b128 v[96:99], v226 offset:96
	ds_read_b128 v[100:103], v226 offset:4704
	s_waitcnt lgkmcnt(6)
	v_mfma_f32_32x32x16_bf16 v[2:17], v[60:63], v[64:67], v[2:17]
	s_waitcnt lgkmcnt(4)
	v_mfma_f32_32x32x16_bf16 v[2:17], v[68:71], v[80:83], v[2:17]
	s_waitcnt lgkmcnt(2)
	v_mfma_f32_32x32x16_bf16 v[2:17], v[88:91], v[92:95], v[2:17]
	s_waitcnt lgkmcnt(0)
	v_mfma_f32_32x32x16_bf16 v[2:17], v[96:99], v[100:103], v[2:17]
	s_waitcnt vmcnt(24)
	ds_write_b128 v225, v[106:109]
	ds_write_b128 v225, v[110:113] offset:1152
	ds_write_b128 v225, v[114:117] offset:2304
	ds_write_b128 v225, v[118:121] offset:3456
	ds_write_b128 v225, v[122:125] offset:4608
	ds_write_b128 v225, v[126:129] offset:5760
	ds_write_b128 v225, v[130:133] offset:6912
	ds_write_b128 v225, v[134:137] offset:8064
	s_waitcnt lgkmcnt(0)
	ds_read_b128 v[60:63], v226
	ds_read_b128 v[64:67], v226 offset:4608
	ds_read_b128 v[68:71], v226 offset:32
	ds_read_b128 v[80:83], v226 offset:4640
	ds_read_b128 v[88:91], v226 offset:64
	ds_read_b128 v[92:95], v226 offset:4672
	ds_read_b128 v[96:99], v226 offset:96
	ds_read_b128 v[100:103], v226 offset:4704
	s_waitcnt lgkmcnt(6)
	v_mfma_f32_32x32x16_bf16 v[2:17], v[60:63], v[64:67], v[2:17]
	s_waitcnt lgkmcnt(4)
	v_mfma_f32_32x32x16_bf16 v[2:17], v[68:71], v[80:83], v[2:17]
	s_waitcnt lgkmcnt(2)
	v_mfma_f32_32x32x16_bf16 v[2:17], v[88:91], v[92:95], v[2:17]
	s_waitcnt lgkmcnt(0)
	v_mfma_f32_32x32x16_bf16 v[2:17], v[96:99], v[100:103], v[2:17]
	s_waitcnt vmcnt(16)
	ds_write_b128 v225, v[138:141]
	ds_write_b128 v225, v[142:145] offset:1152
	ds_write_b128 v225, v[146:149] offset:2304
	ds_write_b128 v225, v[168:171] offset:3456
	ds_write_b128 v225, v[172:175] offset:4608
	ds_write_b128 v225, v[176:179] offset:5760
	ds_write_b128 v225, v[180:183] offset:6912
	ds_write_b128 v225, v[184:187] offset:8064
	s_waitcnt lgkmcnt(0)
	ds_read_b128 v[60:63], v226
	ds_read_b128 v[64:67], v226 offset:4608
	ds_read_b128 v[68:71], v226 offset:32
	ds_read_b128 v[80:83], v226 offset:4640
	ds_read_b128 v[88:91], v226 offset:64
	ds_read_b128 v[92:95], v226 offset:4672
	ds_read_b128 v[96:99], v226 offset:96
	ds_read_b128 v[100:103], v226 offset:4704
	s_waitcnt lgkmcnt(6)
	v_mfma_f32_32x32x16_bf16 v[2:17], v[60:63], v[64:67], v[2:17]
	s_waitcnt lgkmcnt(4)
	v_mfma_f32_32x32x16_bf16 v[2:17], v[68:71], v[80:83], v[2:17]
	s_waitcnt lgkmcnt(2)
	v_mfma_f32_32x32x16_bf16 v[2:17], v[88:91], v[92:95], v[2:17]
	s_waitcnt lgkmcnt(0)
	v_mfma_f32_32x32x16_bf16 v[2:17], v[96:99], v[100:103], v[2:17]
	s_waitcnt vmcnt(8)
	ds_write_b128 v225, v[188:191]
	ds_write_b128 v225, v[192:195] offset:1152
	ds_write_b128 v225, v[196:199] offset:2304
	ds_write_b128 v225, v[200:203] offset:3456
	ds_write_b128 v225, v[204:207] offset:4608
	ds_write_b128 v225, v[208:211] offset:5760
	ds_write_b128 v225, v[212:215] offset:6912
	ds_write_b128 v225, v[216:219] offset:8064
	s_waitcnt lgkmcnt(0)
	ds_read_b128 v[60:63], v226
	ds_read_b128 v[64:67], v226 offset:4608
	ds_read_b128 v[68:71], v226 offset:32
	ds_read_b128 v[80:83], v226 offset:4640
	ds_read_b128 v[88:91], v226 offset:64
	ds_read_b128 v[92:95], v226 offset:4672
	ds_read_b128 v[96:99], v226 offset:96
	ds_read_b128 v[100:103], v226 offset:4704
	s_waitcnt lgkmcnt(6)
	v_mfma_f32_32x32x16_bf16 v[2:17], v[60:63], v[64:67], v[2:17]
	s_waitcnt lgkmcnt(4)
	v_mfma_f32_32x32x16_bf16 v[2:17], v[68:71], v[80:83], v[2:17]
	s_waitcnt lgkmcnt(2)
	v_mfma_f32_32x32x16_bf16 v[2:17], v[88:91], v[92:95], v[2:17]
	s_waitcnt lgkmcnt(0)
	v_mfma_f32_32x32x16_bf16 v[2:17], v[96:99], v[100:103], v[2:17]
	s_waitcnt vmcnt(0)
	ds_write_b128 v225, v[228:231]
	ds_write_b128 v225, v[232:235] offset:1152
	ds_write_b128 v225, v[236:239] offset:2304
	ds_write_b128 v225, v[240:243] offset:3456
	ds_write_b128 v225, v[244:247] offset:4608
	ds_write_b128 v225, v[248:251] offset:5760
	ds_write_b128 v225, v[52:55] offset:6912
	ds_write_b128 v225, v[56:59] offset:8064
	s_waitcnt lgkmcnt(0)
	ds_read_b128 v[60:63], v226
	ds_read_b128 v[64:67], v226 offset:4608
	ds_read_b128 v[68:71], v226 offset:32
	ds_read_b128 v[80:83], v226 offset:4640
	ds_read_b128 v[88:91], v226 offset:64
	ds_read_b128 v[92:95], v226 offset:4672
	ds_read_b128 v[96:99], v226 offset:96
	ds_read_b128 v[100:103], v226 offset:4704
	s_waitcnt lgkmcnt(6)
	v_mfma_f32_32x32x16_bf16 v[2:17], v[60:63], v[64:67], v[2:17]
	s_waitcnt lgkmcnt(4)
	v_mfma_f32_32x32x16_bf16 v[2:17], v[68:71], v[80:83], v[2:17]
	s_waitcnt lgkmcnt(2)
	v_mfma_f32_32x32x16_bf16 v[2:17], v[88:91], v[92:95], v[2:17]
	s_waitcnt lgkmcnt(0)
	v_mfma_f32_32x32x16_bf16 v[2:17], v[96:99], v[100:103], v[2:17]
	s_mov_b32 s38, 0x200
	s_mov_b32 s39, 0
	v_lshl_add_u64 v[70:71], v[22:23], 0, s[38:39]
	v_lshl_add_u64 v[72:73], v[18:19], 0, s[38:39]
	s_movk_i32 s18, 0x100
	s_mov_b64 s[0:1], 0
	s_mov_b64 vcc, exec
	s_nop 10
	ds_write2_b32 v78, v2, v3 offset1:33
	ds_write2_b32 v78, v4, v5 offset0:66 offset1:99
	v_add_u32_e32 v2, 0x400, v78
	ds_write2_b32 v2, v6, v7 offset0:8 offset1:41
	ds_write2_b32 v2, v8, v9 offset0:74 offset1:107
	v_add_u32_e32 v2, 0x800, v78
	ds_write2_b32 v2, v10, v11 offset0:16 offset1:49
	ds_write2_b32 v2, v12, v13 offset0:82 offset1:115
	v_add_u32_e32 v2, 0xc00, v78
	ds_write2_b32 v2, v14, v15 offset0:24 offset1:57
	ds_write2_b32 v2, v16, v17 offset0:90 offset1:123
	s_waitcnt lgkmcnt(0)
	s_barrier
	s_and_saveexec_b64 s[38:39], s[4:5]
	s_cbranch_execz .LBB0_128
	global_load_dword v14, v[26:27], off
	v_add_u32_e32 v2, 0x1080, v79
	v_add_u32_e32 v3, 0x2100, v79
	v_add_u32_e32 v4, 0x3180, v79
	v_add_u32_e32 v5, 0x1090, v79
	ds_read2_b32 v[16:17], v2 offset1:1
	ds_read2_b32 v[50:51], v3 offset1:1
	ds_read2_b32 v[52:53], v4 offset1:1
	ds_read2_b32 v[12:13], v5 offset1:1
	v_add_u32_e32 v2, 0x2110, v79
	v_add_u32_e32 v3, 0x3190, v79
	ds_read2_b32 v[62:63], v79 offset1:1
	ds_read2_b32 v[56:57], v79 offset0:4 offset1:5
	ds_read2_b32 v[10:11], v79 offset0:6 offset1:7
	ds_read2_b32 v[54:55], v79 offset0:2 offset1:3
	v_add_u32_e32 v4, 0x1088, v79
	v_add_u32_e32 v5, 0x2108, v79
	ds_read2_b32 v[64:65], v2 offset1:1
	ds_read2_b32 v[66:67], v3 offset1:1
	ds_read2_b32 v[58:59], v4 offset1:1
	ds_read2_b32 v[60:61], v5 offset1:1
	v_add_u32_e32 v2, 0x3188, v79
	v_add_u32_e32 v3, 0x1098, v79
	v_add_u32_e32 v4, 0x2118, v79
	v_add_u32_e32 v5, 0x3198, v79
	ds_read2_b32 v[74:75], v2 offset1:1
	ds_read2_b32 v[68:69], v3 offset1:1
	ds_read2_b32 v[70:71], v4 offset1:1
	ds_read2_b32 v[72:73], v5 offset1:1
	s_ashr_i32 s18, s33, 3
	s_and_b32 s37, s37, 0xe0
	s_cmp_gt_i32 s18, 7
	s_cselect_b64 s[0:1], -1, 0
	v_or_b32_e32 v80, s37, v77
	v_mov_b32_e32 v2, 0
	s_and_b64 vcc, exec, s[0:1]
	v_mov_b32_e32 v18, 0
	v_mov_b32_e32 v3, 0
	v_mov_b32_e32 v19, 0
	v_mov_b32_e32 v6, 0
	v_mov_b32_e32 v4, 0
	v_mov_b32_e32 v7, 0
	v_mov_b32_e32 v5, 0
	s_cbranch_vccnz .LBB0_134
	v_and_b32_e32 v2, 0x78, v80
	v_lshlrev_b32_e32 v20, 2, v2
	v_lshl_add_u64 v[6:7], v[28:29], 0, v[20:21]
	global_load_dwordx4 v[2:5], v[6:7], off
	s_nop 0
	global_load_dwordx4 v[6:9], v[6:7], off offset:16
	s_waitcnt vmcnt(1)
	v_mov_b32_e32 v18, v3
	v_mov_b32_e32 v3, v4
	v_mov_b32_e32 v19, v5
	s_waitcnt vmcnt(0)
	v_mov_b32_e32 v4, v7
	v_mov_b32_e32 v7, v8
	v_mov_b32_e32 v5, v9

.LBB0_851:
	v_readlane_b32 s1, v255, 40
	s_cmp_lt_u32 s1, 8
	s_cbranch_scc0 .Lsmp_med
	s_cmp_eq_u32 s0, 0
	s_cselect_b32 s0, 16, 0
	s_add_i32 s0, s0, s1
	s_branch .Lsmp_done
.Lsmp_med:
	s_cmp_lg_u32 s0, 0
	s_cselect_b32 s0, 1, 0
	s_lshl_b32 s1, s1, 1
	s_add_i32 s0, s0, s1
	s_sub_i32 s0, s0, 8
.Lsmp_done:
	s_and_b32 s1, s0, 7
	v_readlane_b32 s2, v255, 13
	s_or_b32 s1, s1, s2
	s_ashr_i32 s0, s0, 3
	s_mul_i32 s1, s1, 3
	s_add_i32 s1, s1, s0
	s_mul_hi_i32 s0, s1, 0x55555556
	s_lshr_b32 s2, s0, 31
	s_add_i32 s0, s0, s2
	s_mul_i32 s2, s0, 3
	s_sub_i32 s2, s1, s2
	s_ashr_i32 s1, s0, 3
	s_add_i32 s14, s1, 0x2000
	v_writelane_b32 v255, s2, 41
	s_lshl_b32 s24, s2, 1
	s_mov_b32 s2, s14
	v_writelane_b32 v255, s2, 43
	s_ashr_i32 s15, s14, 31
	s_and_b32 s19, s0, 7
	v_writelane_b32 v255, s3, 44
	s_ashr_i32 s0, s0, 6
	s_and_b32 s16, s1, 7
	s_lshl_b32 s17, -1, s24
	s_lshl_b64 s[2:3], s[14:15], 11
	v_readlane_b32 s14, v255, 26
	v_readlane_b32 s15, v255, 27
	s_add_u32 s1, s14, s2
	s_addc_u32 s15, s15, s3
	s_lshl_b32 s2, s19, 8
	s_add_u32 s14, s1, s2
	s_addc_u32 s15, s15, 0
	s_ashr_i32 s1, s0, 31
	s_lshl_b64 s[28:29], s[0:1], 23
	s_lshl_b32 s1, s16, 12
	s_or_b32 s1, s28, s1
	s_add_u32 s1, s1, 0x800000
	s_addc_u32 s18, s29, 0
	v_readlane_b32 s36, v255, 22
	global_load_dword v92, v143, s[14:15]
	v_readlane_b32 s37, v255, 23
	s_add_u32 s14, s36, s1
	s_addc_u32 s15, s37, s18
	s_lshl_b32 s20, s19, 9
	s_add_u32 s14, s14, s20
	v_readlane_b32 s38, v255, 24
	s_addc_u32 s15, s15, 0
	v_readlane_b32 s39, v255, 25
	s_add_u32 s1, s38, s1
	v_lshl_add_u64 v[12:13], s[14:15], 0, v[10:11]
	s_addc_u32 s15, s39, s18
	s_add_u32 s14, s1, s20
	s_addc_u32 s15, s15, 0
	s_lshl_b32 s30, s0, 3
	v_lshl_add_u64 v[14:15], s[14:15], 0, v[10:11]
	s_or_b32 s14, s16, 0x800
	s_add_i32 s25, s30, 0x1800
	s_add_i32 s0, s25, s14
	s_mov_b32 s3, s21
	s_ashr_i32 s1, s0, 31
	v_lshl_add_u64 v[16:17], v[2:3], 0, s[2:3]
	s_lshl_b64 s[2:3], s[0:1], 11
	v_lshl_add_u64 v[18:19], v[16:17], 0, s[2:3]
	global_load_dword v93, v[18:19], off
	s_add_i32 s36, s14, s17
	s_cmpk_lt_i32 s36, 0x800
	s_cselect_b64 s[50:51], -1, 0
	s_cmpk_gt_i32 s36, 0x7ff
	s_mov_b64 s[0:1], -1
	s_cbranch_scc1 .LBB0_853
	s_ashr_i32 s37, s36, 31
	s_lshl_b64 s[0:1], s[36:37], 12
	v_lshl_add_u64 v[18:19], v[6:7], 0, s[0:1]
	v_lshl_add_u64 v[18:19], v[18:19], 0, s[28:29]
	v_lshl_add_u64 v[18:19], v[18:19], 0, s[20:21]
	global_load_dwordx2 v[18:19], v[18:19], off
	s_mov_b64 s[0:1], 0

.LBB0_1053:
	s_or_b64 exec, exec, s[2:3]
	v_readlane_b32 s0, v255, 3
	v_readlane_b32 s1, v255, 4
	s_waitcnt lgkmcnt(0)
	s_barrier
	s_load_dwordx2 s[8:9], s[0:1], 0xd0
	s_load_dwordx4 s[12:15], s[0:1], 0x0
	s_lshr_b32 s0, s94, 1
	v_mov_b32_e32 v2, v0
	s_waitcnt lgkmcnt(0)
	s_add_u32 s2, s8, 0x7300000
	s_addc_u32 s3, s9, 0
	s_add_u32 s40, s8, 0x2a00000
	s_addc_u32 s41, s9, 0
	s_cmp_lt_i32 s0, 64
	s_cselect_b64 s[50:51], -1, 0
	s_cmp_gt_i32 s0, 63
	v_readfirstlane_b32 s0, v2
	s_cbranch_scc1 .LBB0_1061
	s_ashr_i32 s4, s0, 6
	s_ashr_i32 s0, s0, 3
	s_movk_i32 s1, 0xffe0
	v_mov_b32_e32 v4, s0
	v_bfi_b32 v4, s1, v4, v2
	v_ashrrev_i32_e32 v5, 31, v4
	v_lshlrev_b64 v[4:5], 12, v[4:5]
	s_lshl_b32 s0, s4, 10
	v_bfe_u32 v3, v2, 5, 1
	v_lshl_add_u64 v[4:5], s[8:9], 0, v[4:5]
	s_and_b32 s10, s0, 0xc00
	s_mov_b32 s11, 0
	v_lshl_add_u64 v[4:5], v[4:5], 0, s[10:11]
	v_lshlrev_b32_e32 v18, 4, v3
	v_mov_b32_e32 v19, 0
	v_lshl_add_u64 v[4:5], v[4:5], 0, v[18:19]
	s_mov_b64 s[0:1], 0x7200000
	v_lshl_add_u64 v[20:21], v[4:5], 0, s[0:1]
	s_add_u32 s0, s40, s10
	s_addc_u32 s1, s41, 0
	v_lshl_add_u64 v[22:23], s[0:1], 0, v[18:19]
	s_lshl_b32 s0, s4, 5
	v_lshl_or_b32 v8, v3, 2, s0
	s_movk_i32 s0, 0x100
	v_and_b32_e32 v32, 31, v2
	v_lshrrev_b32_e32 v220, 7, v2
	s_and_b32 s66, s94, 1
	v_cmp_eq_u32_e64 s[4:5], s66, v220
	v_ashrrev_i32_e32 v4, 2, v2
	v_and_b32_e32 v5, 3, v2
	v_and_b32_e32 v2, 0x3fffff80, v2
	v_and_or_b32 v10, v4, 31, v2
	v_lshl_add_u32 v11, v5, 5, 0
	v_lshlrev_b32_e32 v33, 3, v5
	v_add_u32_e32 v2, 0x2000, v4
	v_cmp_gt_i32_e32 vcc, 0, v4
	v_cmp_eq_u32_e64 s[6:7], 0, v5
	v_ashrrev_i32_e32 v5, 31, v4
	v_cndmask_b32_e32 v6, v4, v2, vcc
	v_lshl_add_u64 v[4:5], v[4:5], 2, s[8:9]
	s_mov_b64 s[0:1], 0x18000
	v_ashrrev_i32_e32 v3, 31, v2
	v_lshl_add_u64 v[24:25], v[4:5], 0, s[0:1]
	v_mov_b32_e32 v4, s15
	v_mov_b32_e32 v5, s13
	v_cndmask_b32_e32 v7, 0, v3, vcc
	s_movk_i32 s0, 0x84
	v_cndmask_b32_e32 v5, v4, v5, vcc
	v_mov_b32_e32 v4, s14
	v_mov_b32_e32 v12, s12
	v_lshl_add_u32 v9, v32, 2, 0
	v_lshlrev_b64 v[6:7], 13, v[6:7]
	v_lshlrev_b64 v[2:3], 12, v[2:3]
	v_mul_lo_u32 v8, v8, s0
	v_mul_lo_u32 v10, v10, s0
	v_cndmask_b32_e32 v4, v4, v12, vcc
	v_lshl_add_u64 v[26:27], v[4:5], 0, v[6:7]
	v_lshl_add_u64 v[28:29], s[2:3], 0, v[2:3]
	v_add_u32_e32 v34, v9, v8
	v_add_u32_e32 v35, v11, v10
	v_mbcnt_hi_u32_b32 v36, -1, v1
	s_lshr_b32 s18, s94, 1
	s_branch .LBB0_1056

.LBB0_1056:
	s_lshl_b32 s16, s18, 5
	v_or_b32_e32 v2, s16, v32
	v_ashrrev_i32_e32 v3, 31, v2
	v_lshlrev_b64 v[2:3], 12, v[2:3]
	v_lshl_add_u64 v[30:31], v[22:23], 0, v[2:3]
	s_mov_b64 s[0:1], -1
	s_mov_b32 s10, s11
	v_mov_b32_e32 v2, 0
	v_mov_b32_e32 v3, v19
	v_mov_b32_e32 v4, v19
	v_mov_b32_e32 v5, v19
	v_mov_b32_e32 v6, v19
	v_mov_b32_e32 v7, v19
	v_mov_b32_e32 v8, v19
	v_mov_b32_e32 v9, v19
	v_mov_b32_e32 v10, v19
	v_mov_b32_e32 v11, v19
	v_mov_b32_e32 v12, v19
	v_mov_b32_e32 v13, v19
	v_mov_b32_e32 v14, v19
	v_mov_b32_e32 v15, v19
	v_mov_b32_e32 v16, v19
	v_mov_b32_e32 v17, v19
	v_readfirstlane_b32 s66, v20
	v_readfirstlane_b32 s67, v21
	v_readfirstlane_b32 s68, v30
	v_readfirstlane_b32 s69, v31
	v_readfirstlane_b32 s70, v0
	v_mbcnt_lo_u32_b32 v220, -1, 0
	v_mbcnt_hi_u32_b32 v220, -1, v220
	s_lshr_b32 s70, s70, 6
	s_lshr_b32 s71, s70, 2
	s_and_b32 s74, s94, 1
	s_cmp_lg_u32 s71, s74
	s_cbranch_scc1 .Lsk3_end_1
	s_mul_i32 s70, s70, 9216
	s_add_i32 s70, s70, 36864
	v_lshrrev_b32_e32 v221, 3, v220
	v_and_b32_e32 v222, 7, v220
	v_lshlrev_b32_e32 v224, 12, v221
	v_lshl_add_u32 v224, v222, 4, v224
	v_mul_u32_u24_e32 v225, 144, v221
	v_lshl_add_u32 v225, v222, 4, v225
	v_add_u32_e32 v225, s70, v225
	v_and_b32_e32 v221, 31, v220
	v_lshrrev_b32_e32 v222, 5, v220
	v_mul_u32_u24_e32 v226, 144, v221
	v_lshl_add_u32 v226, v222, 4, v226
	v_add_u32_e32 v226, s70, v226
	s_add_u32 s72, s66, 0
	s_addc_u32 s73, s67, 0
	s_add_u32 s74, s68, 0
	s_addc_u32 s75, s69, 0
	global_load_dwordx4 v[106:109], v224, s[72:73]
	global_load_dwordx4 v[122:125], v224, s[74:75]
	s_add_u32 s72, s66, 32768
	s_addc_u32 s73, s67, 0
	s_add_u32 s74, s68, 32768
	s_addc_u32 s75, s69, 0
	global_load_dwordx4 v[110:113], v224, s[72:73]
	global_load_dwordx4 v[126:129], v224, s[74:75]
	s_add_u32 s72, s66, 65536
	s_addc_u32 s73, s67, 0
	s_add_u32 s74, s68, 65536
	s_addc_u32 s75, s69, 0
	global_load_dwordx4 v[114:117], v224, s[72:73]
	global_load_dwordx4 v[130:133], v224, s[74:75]
	s_add_u32 s72, s66, 98304
	s_addc_u32 s73, s67, 0
	s_add_u32 s74, s68, 98304
	s_addc_u32 s75, s69, 0
	global_load_dwordx4 v[118:121], v224, s[72:73]
	global_load_dwordx4 v[134:137], v224, s[74:75]
	s_add_u32 s72, s66, 128
	s_addc_u32 s73, s67, 0
	s_add_u32 s74, s68, 128
	s_addc_u32 s75, s69, 0
	global_load_dwordx4 v[138:141], v224, s[72:73]
	global_load_dwordx4 v[172:175], v224, s[74:75]
	s_add_u32 s72, s66, 32896
	s_addc_u32 s73, s67, 0
	s_add_u32 s74, s68, 32896
	s_addc_u32 s75, s69, 0
	global_load_dwordx4 v[142:145], v224, s[72:73]
	global_load_dwordx4 v[176:179], v224, s[74:75]
	s_add_u32 s72, s66, 65664
	s_addc_u32 s73, s67, 0
	s_add_u32 s74, s68, 65664
	s_addc_u32 s75, s69, 0
	global_load_dwordx4 v[146:149], v224, s[72:73]
	global_load_dwordx4 v[180:183], v224, s[74:75]
	s_add_u32 s72, s66, 98432
	s_addc_u32 s73, s67, 0
	s_add_u32 s74, s68, 98432
	s_addc_u32 s75, s69, 0
	global_load_dwordx4 v[168:171], v224, s[72:73]
	global_load_dwordx4 v[184:187], v224, s[74:75]
	s_add_u32 s72, s66, 256
	s_addc_u32 s73, s67, 0
	s_add_u32 s74, s68, 256
	s_addc_u32 s75, s69, 0
	global_load_dwordx4 v[188:191], v224, s[72:73]
	global_load_dwordx4 v[204:207], v224, s[74:75]
	s_add_u32 s72, s66, 33024
	s_addc_u32 s73, s67, 0
	s_add_u32 s74, s68, 33024
	s_addc_u32 s75, s69, 0
	global_load_dwordx4 v[192:195], v224, s[72:73]
	global_load_dwordx4 v[208:211], v224, s[74:75]
	s_add_u32 s72, s66, 65792
	s_addc_u32 s73, s67, 0
	s_add_u32 s74, s68, 65792
	s_addc_u32 s75, s69, 0
	global_load_dwordx4 v[196:199], v224, s[72:73]
	global_load_dwordx4 v[212:215], v224, s[74:75]
	s_add_u32 s72, s66, 98560
	s_addc_u32 s73, s67, 0
	s_add_u32 s74, s68, 98560
	s_addc_u32 s75, s69, 0
	global_load_dwordx4 v[200:203], v224, s[72:73]
	global_load_dwordx4 v[216:219], v224, s[74:75]
	s_add_u32 s72, s66, 384
	s_addc_u32 s73, s67, 0
	s_add_u32 s74, s68, 384
	s_addc_u32 s75, s69, 0
	global_load_dwordx4 v[228:231], v224, s[72:73]
	global_load_dwordx4 v[244:247], v224, s[74:75]
	s_add_u32 s72, s66, 33152
	s_addc_u32 s73, s67, 0
	s_add_u32 s74, s68, 33152
	s_addc_u32 s75, s69, 0
	global_load_dwordx4 v[232:235], v224, s[72:73]
	global_load_dwordx4 v[248:251], v224, s[74:75]
	s_add_u32 s72, s66, 65920
	s_addc_u32 s73, s67, 0
	s_add_u32 s74, s68, 65920
	s_addc_u32 s75, s69, 0
	global_load_dwordx4 v[236:239], v224, s[72:73]
	global_load_dwordx4 v[52:55], v224, s[74:75]
	s_add_u32 s72, s66, 98688
	s_addc_u32 s73, s67, 0
	s_add_u32 s74, s68, 98688
	s_addc_u32 s75, s69, 0
	global_load_dwordx4 v[240:243], v224, s[72:73]
	global_load_dwordx4 v[56:59], v224, s[74:75]
	s_waitcnt vmcnt(24)
	ds_write_b128 v225, v[106:109]
	ds_write_b128 v225, v[110:113] offset:1152
	ds_write_b128 v225, v[114:117] offset:2304
	ds_write_b128 v225, v[118:121] offset:3456
	ds_write_b128 v225, v[122:125] offset:4608
	ds_write_b128 v225, v[126:129] offset:5760
	ds_write_b128 v225, v[130:133] offset:6912
	ds_write_b128 v225, v[134:137] offset:8064
	s_nop 1
	s_add_u32 s72, s66, 512
	s_addc_u32 s73, s67, 0
	s_add_u32 s74, s68, 512
	s_addc_u32 s75, s69, 0
	global_load_dwordx4 v[106:109], v224, s[72:73]
	global_load_dwordx4 v[122:125], v224, s[74:75]
	s_add_u32 s72, s66, 33280
	s_addc_u32 s73, s67, 0
	s_add_u32 s74, s68, 33280
	s_addc_u32 s75, s69, 0
	global_load_dwordx4 v[110:113], v224, s[72:73]
	global_load_dwordx4 v[126:129], v224, s[74:75]
	s_add_u32 s72, s66, 66048
	s_addc_u32 s73, s67, 0
	s_add_u32 s74, s68, 66048
	s_addc_u32 s75, s69, 0
	global_load_dwordx4 v[114:117], v224, s[72:73]
	global_load_dwordx4 v[130:133], v224, s[74:75]
	s_add_u32 s72, s66, 98816
	s_addc_u32 s73, s67, 0
	s_add_u32 s74, s68, 98816
	s_addc_u32 s75, s69, 0
	global_load_dwordx4 v[118:121], v224, s[72:73]
	global_load_dwordx4 v[134:137], v224, s[74:75]
	s_waitcnt lgkmcnt(0)
	ds_read_b128 v[60:63], v226
	ds_read_b128 v[64:67], v226 offset:4608
	ds_read_b128 v[68:71], v226 offset:32
	ds_read_b128 v[80:83], v226 offset:4640
	ds_read_b128 v[88:91], v226 offset:64
	ds_read_b128 v[92:95], v226 offset:4672
	ds_read_b128 v[96:99], v226 offset:96
	ds_read_b128 v[100:103], v226 offset:4704
	s_waitcnt lgkmcnt(6)
	v_mfma_f32_32x32x16_bf16 v[2:17], v[60:63], v[64:67], v[2:17]
	s_waitcnt lgkmcnt(4)
	v_mfma_f32_32x32x16_bf16 v[2:17], v[68:71], v[80:83], v[2:17]
	s_waitcnt lgkmcnt(2)
	v_mfma_f32_32x32x16_bf16 v[2:17], v[88:91], v[92:95], v[2:17]
	s_waitcnt lgkmcnt(0)
	v_mfma_f32_32x32x16_bf16 v[2:17], v[96:99], v[100:103], v[2:17]
	s_waitcnt vmcnt(24)
	ds_write_b128 v225, v[138:141]
	ds_write_b128 v225, v[142:145] offset:1152
	ds_write_b128 v225, v[146:149] offset:2304
	ds_write_b128 v225, v[168:171] offset:3456
	ds_write_b128 v225, v[172:175] offset:4608
	ds_write_b128 v225, v[176:179] offset:5760
	ds_write_b128 v225, v[180:183] offset:6912
	ds_write_b128 v225, v[184:187] offset:8064
	s_nop 1
	s_add_u32 s72, s66, 640
	s_addc_u32 s73, s67, 0
	s_add_u32 s74, s68, 640
	s_addc_u32 s75, s69, 0
	global_load_dwordx4 v[138:141], v224, s[72:73]
	global_load_dwordx4 v[172:175], v224, s[74:75]
	s_add_u32 s72, s66, 33408
	s_addc_u32 s73, s67, 0
	s_add_u32 s74, s68, 33408
	s_addc_u32 s75, s69, 0
	global_load_dwordx4 v[142:145], v224, s[72:73]
	global_load_dwordx4 v[176:179], v224, s[74:75]
	s_add_u32 s72, s66, 66176
	s_addc_u32 s73, s67, 0
	s_add_u32 s74, s68, 66176
	s_addc_u32 s75, s69, 0
	global_load_dwordx4 v[146:149], v224, s[72:73]
	global_load_dwordx4 v[180:183], v224, s[74:75]
	s_add_u32 s72, s66, 98944
	s_addc_u32 s73, s67, 0
	s_add_u32 s74, s68, 98944
	s_addc_u32 s75, s69, 0
	global_load_dwordx4 v[168:171], v224, s[72:73]
	global_load_dwordx4 v[184:187], v224, s[74:75]
	s_waitcnt lgkmcnt(0)
	ds_read_b128 v[60:63], v226
	ds_read_b128 v[64:67], v226 offset:4608
	ds_read_b128 v[68:71], v226 offset:32
	ds_read_b128 v[80:83], v226 offset:4640
	ds_read_b128 v[88:91], v226 offset:64
	ds_read_b128 v[92:95], v226 offset:4672
	ds_read_b128 v[96:99], v226 offset:96
	ds_read_b128 v[100:103], v226 offset:4704
	s_waitcnt lgkmcnt(6)
	v_mfma_f32_32x32x16_bf16 v[2:17], v[60:63], v[64:67], v[2:17]
	s_waitcnt lgkmcnt(4)
	v_mfma_f32_32x32x16_bf16 v[2:17], v[68:71], v[80:83], v[2:17]
	s_waitcnt lgkmcnt(2)
	v_mfma_f32_32x32x16_bf16 v[2:17], v[88:91], v[92:95], v[2:17]
	s_waitcnt lgkmcnt(0)
	v_mfma_f32_32x32x16_bf16 v[2:17], v[96:99], v[100:103], v[2:17]
	s_waitcnt vmcnt(24)
	ds_write_b128 v225, v[188:191]
	ds_write_b128 v225, v[192:195] offset:1152
	ds_write_b128 v225, v[196:199] offset:2304
	ds_write_b128 v225, v[200:203] offset:3456
	ds_write_b128 v225, v[204:207] offset:4608
	ds_write_b128 v225, v[208:211] offset:5760
	ds_write_b128 v225, v[212:215] offset:6912
	ds_write_b128 v225, v[216:219] offset:8064
	s_nop 1
	s_add_u32 s72, s66, 768
	s_addc_u32 s73, s67, 0
	s_add_u32 s74, s68, 768
	s_addc_u32 s75, s69, 0
	global_load_dwordx4 v[188:191], v224, s[72:73]
	global_load_dwordx4 v[204:207], v224, s[74:75]
	s_add_u32 s72, s66, 33536
	s_addc_u32 s73, s67, 0
	s_add_u32 s74, s68, 33536
	s_addc_u32 s75, s69, 0
	global_load_dwordx4 v[192:195], v224, s[72:73]
	global_load_dwordx4 v[208:211], v224, s[74:75]
	s_add_u32 s72, s66, 66304
	s_addc_u32 s73, s67, 0
	s_add_u32 s74, s68, 66304
	s_addc_u32 s75, s69, 0
	global_load_dwordx4 v[196:199], v224, s[72:73]
	global_load_dwordx4 v[212:215], v224, s[74:75]
	s_add_u32 s72, s66, 99072
	s_addc_u32 s73, s67, 0
	s_add_u32 s74, s68, 99072
	s_addc_u32 s75, s69, 0
	global_load_dwordx4 v[200:203], v224, s[72:73]
	global_load_dwordx4 v[216:219], v224, s[74:75]
	s_waitcnt lgkmcnt(0)
	ds_read_b128 v[60:63], v226
	ds_read_b128 v[64:67], v226 offset:4608
	ds_read_b128 v[68:71], v226 offset:32
	ds_read_b128 v[80:83], v226 offset:4640
	ds_read_b128 v[88:91], v226 offset:64
	ds_read_b128 v[92:95], v226 offset:4672
	ds_read_b128 v[96:99], v226 offset:96
	ds_read_b128 v[100:103], v226 offset:4704
	s_waitcnt lgkmcnt(6)
	v_mfma_f32_32x32x16_bf16 v[2:17], v[60:63], v[64:67], v[2:17]
	s_waitcnt lgkmcnt(4)
	v_mfma_f32_32x32x16_bf16 v[2:17], v[68:71], v[80:83], v[2:17]
	s_waitcnt lgkmcnt(2)
	v_mfma_f32_32x32x16_bf16 v[2:17], v[88:91], v[92:95], v[2:17]
	s_waitcnt lgkmcnt(0)
	v_mfma_f32_32x32x16_bf16 v[2:17], v[96:99], v[100:103], v[2:17]
	s_waitcnt vmcnt(24)
	ds_write_b128 v225, v[228:231]
	ds_write_b128 v225, v[232:235] offset:1152
	ds_write_b128 v225, v[236:239] offset:2304
	ds_write_b128 v225, v[240:243] offset:3456
	ds_write_b128 v225, v[244:247] offset:4608
	ds_write_b128 v225, v[248:251] offset:5760
	ds_write_b128 v225, v[52:55] offset:6912
	ds_write_b128 v225, v[56:59] offset:8064
	s_nop 1
	s_add_u32 s72, s66, 896
	s_addc_u32 s73, s67, 0
	s_add_u32 s74, s68, 896
	s_addc_u32 s75, s69, 0
	global_load_dwordx4 v[228:231], v224, s[72:73]
	global_load_dwordx4 v[244:247], v224, s[74:75]
	s_add_u32 s72, s66, 33664
	s_addc_u32 s73, s67, 0
	s_add_u32 s74, s68, 33664
	s_addc_u32 s75, s69, 0
	global_load_dwordx4 v[232:235], v224, s[72:73]
	global_load_dwordx4 v[248:251], v224, s[74:75]
	s_add_u32 s72, s66, 66432
	s_addc_u32 s73, s67, 0
	s_add_u32 s74, s68, 66432
	s_addc_u32 s75, s69, 0
	global_load_dwordx4 v[236:239], v224, s[72:73]
	global_load_dwordx4 v[52:55], v224, s[74:75]
	s_add_u32 s72, s66, 99200
	s_addc_u32 s73, s67, 0
	s_add_u32 s74, s68, 99200
	s_addc_u32 s75, s69, 0
	global_load_dwordx4 v[240:243], v224, s[72:73]
	global_load_dwordx4 v[56:59], v224, s[74:75]
	s_waitcnt lgkmcnt(0)
	ds_read_b128 v[60:63], v226
	ds_read_b128 v[64:67], v226 offset:4608
	ds_read_b128 v[68:71], v226 offset:32
	ds_read_b128 v[80:83], v226 offset:4640
	ds_read_b128 v[88:91], v226 offset:64
	ds_read_b128 v[92:95], v226 offset:4672
	ds_read_b128 v[96:99], v226 offset:96
	ds_read_b128 v[100:103], v226 offset:4704
	s_waitcnt lgkmcnt(6)
	v_mfma_f32_32x32x16_bf16 v[2:17], v[60:63], v[64:67], v[2:17]
	s_waitcnt lgkmcnt(4)
	v_mfma_f32_32x32x16_bf16 v[2:17], v[68:71], v[80:83], v[2:17]
	s_waitcnt lgkmcnt(2)
	v_mfma_f32_32x32x16_bf16 v[2:17], v[88:91], v[92:95], v[2:17]
	s_waitcnt lgkmcnt(0)
	v_mfma_f32_32x32x16_bf16 v[2:17], v[96:99], v[100:103], v[2:17]
	s_waitcnt vmcnt(24)
	ds_write_b128 v225, v[106:109]
	ds_write_b128 v225, v[110:113] offset:1152
	ds_write_b128 v225, v[114:117] offset:2304
	ds_write_b128 v225, v[118:121] offset:3456
	ds_write_b128 v225, v[122:125] offset:4608
	ds_write_b128 v225, v[126:129] offset:5760
	ds_write_b128 v225, v[130:133] offset:6912
	ds_write_b128 v225, v[134:137] offset:8064
	s_waitcnt lgkmcnt(0)
	ds_read_b128 v[60:63], v226
	ds_read_b128 v[64:67], v226 offset:4608
	ds_read_b128 v[68:71], v226 offset:32
	ds_read_b128 v[80:83], v226 offset:4640
	ds_read_b128 v[88:91], v226 offset:64
	ds_read_b128 v[92:95], v226 offset:4672
	ds_read_b128 v[96:99], v226 offset:96
	ds_read_b128 v[100:103], v226 offset:4704
	s_waitcnt lgkmcnt(6)
	v_mfma_f32_32x32x16_bf16 v[2:17], v[60:63], v[64:67], v[2:17]
	s_waitcnt lgkmcnt(4)
	v_mfma_f32_32x32x16_bf16 v[2:17], v[68:71], v[80:83], v[2:17]
	s_waitcnt lgkmcnt(2)
	v_mfma_f32_32x32x16_bf16 v[2:17], v[88:91], v[92:95], v[2:17]
	s_waitcnt lgkmcnt(0)
	v_mfma_f32_32x32x16_bf16 v[2:17], v[96:99], v[100:103], v[2:17]
	s_waitcnt vmcnt(16)
	ds_write_b128 v225, v[138:141]
	ds_write_b128 v225, v[142:145] offset:1152
	ds_write_b128 v225, v[146:149] offset:2304
	ds_write_b128 v225, v[168:171] offset:3456
	ds_write_b128 v225, v[172:175] offset:4608
	ds_write_b128 v225, v[176:179] offset:5760
	ds_write_b128 v225, v[180:183] offset:6912
	ds_write_b128 v225, v[184:187] offset:8064
	s_waitcnt lgkmcnt(0)
	ds_read_b128 v[60:63], v226
	ds_read_b128 v[64:67], v226 offset:4608
	ds_read_b128 v[68:71], v226 offset:32
	ds_read_b128 v[80:83], v226 offset:4640
	ds_read_b128 v[88:91], v226 offset:64
	ds_read_b128 v[92:95], v226 offset:4672
	ds_read_b128 v[96:99], v226 offset:96
	ds_read_b128 v[100:103], v226 offset:4704
	s_waitcnt lgkmcnt(6)
	v_mfma_f32_32x32x16_bf16 v[2:17], v[60:63], v[64:67], v[2:17]
	s_waitcnt lgkmcnt(4)
	v_mfma_f32_32x32x16_bf16 v[2:17], v[68:71], v[80:83], v[2:17]
	s_waitcnt lgkmcnt(2)
	v_mfma_f32_32x32x16_bf16 v[2:17], v[88:91], v[92:95], v[2:17]
	s_waitcnt lgkmcnt(0)
	v_mfma_f32_32x32x16_bf16 v[2:17], v[96:99], v[100:103], v[2:17]
	s_waitcnt vmcnt(8)
	ds_write_b128 v225, v[188:191]
	ds_write_b128 v225, v[192:195] offset:1152
	ds_write_b128 v225, v[196:199] offset:2304
	ds_write_b128 v225, v[200:203] offset:3456
	ds_write_b128 v225, v[204:207] offset:4608
	ds_write_b128 v225, v[208:211] offset:5760
	ds_write_b128 v225, v[212:215] offset:6912
	ds_write_b128 v225, v[216:219] offset:8064
	s_waitcnt lgkmcnt(0)
	ds_read_b128 v[60:63], v226
	ds_read_b128 v[64:67], v226 offset:4608
	ds_read_b128 v[68:71], v226 offset:32
	ds_read_b128 v[80:83], v226 offset:4640
	ds_read_b128 v[88:91], v226 offset:64
	ds_read_b128 v[92:95], v226 offset:4672
	ds_read_b128 v[96:99], v226 offset:96
	ds_read_b128 v[100:103], v226 offset:4704
	s_waitcnt lgkmcnt(6)
	v_mfma_f32_32x32x16_bf16 v[2:17], v[60:63], v[64:67], v[2:17]
	s_waitcnt lgkmcnt(4)
	v_mfma_f32_32x32x16_bf16 v[2:17], v[68:71], v[80:83], v[2:17]
	s_waitcnt lgkmcnt(2)
	v_mfma_f32_32x32x16_bf16 v[2:17], v[88:91], v[92:95], v[2:17]
	s_waitcnt lgkmcnt(0)
	v_mfma_f32_32x32x16_bf16 v[2:17], v[96:99], v[100:103], v[2:17]
	s_waitcnt vmcnt(0)
	ds_write_b128 v225, v[228:231]
	ds_write_b128 v225, v[232:235] offset:1152
	ds_write_b128 v225, v[236:239] offset:2304
	ds_write_b128 v225, v[240:243] offset:3456
	ds_write_b128 v225, v[244:247] offset:4608
	ds_write_b128 v225, v[248:251] offset:5760
	ds_write_b128 v225, v[52:55] offset:6912
	ds_write_b128 v225, v[56:59] offset:8064
	s_waitcnt lgkmcnt(0)
	ds_read_b128 v[60:63], v226
	ds_read_b128 v[64:67], v226 offset:4608
	ds_read_b128 v[68:71], v226 offset:32
	ds_read_b128 v[80:83], v226 offset:4640
	ds_read_b128 v[88:91], v226 offset:64
	ds_read_b128 v[92:95], v226 offset:4672
	ds_read_b128 v[96:99], v226 offset:96
	ds_read_b128 v[100:103], v226 offset:4704
	s_waitcnt lgkmcnt(6)
	v_mfma_f32_32x32x16_bf16 v[2:17], v[60:63], v[64:67], v[2:17]
	s_waitcnt lgkmcnt(4)
	v_mfma_f32_32x32x16_bf16 v[2:17], v[68:71], v[80:83], v[2:17]
	s_waitcnt lgkmcnt(2)
	v_mfma_f32_32x32x16_bf16 v[2:17], v[88:91], v[92:95], v[2:17]
	s_waitcnt lgkmcnt(0)
	v_mfma_f32_32x32x16_bf16 v[2:17], v[96:99], v[100:103], v[2:17]
.Lsk3_end_1:
	s_mov_b32 s20, 0x200
	s_mov_b32 s21, 0
	v_lshl_add_u64 v[58:59], v[20:21], 0, s[20:21]
	v_lshl_add_u64 v[60:61], v[30:31], 0, s[20:21]
	s_movk_i32 s10, 0x100
	s_mov_b64 s[0:1], 0
	s_mov_b64 vcc, exec
	s_nop 10
	ds_write2_b32 v34, v2, v3 offset1:33
	ds_write2_b32 v34, v4, v5 offset0:66 offset1:99
	v_add_u32_e32 v2, 0x400, v34
	ds_write2_b32 v2, v6, v7 offset0:8 offset1:41
	ds_write2_b32 v2, v8, v9 offset0:74 offset1:107
	v_add_u32_e32 v2, 0x800, v34
	ds_write2_b32 v2, v10, v11 offset0:16 offset1:49
	ds_write2_b32 v2, v12, v13 offset0:82 offset1:115
	v_add_u32_e32 v2, 0xc00, v34
	ds_write2_b32 v2, v14, v15 offset0:24 offset1:57
	ds_write2_b32 v2, v16, v17 offset0:90 offset1:123
	s_waitcnt lgkmcnt(0)
	s_barrier
	s_and_saveexec_b64 s[0:1], s[4:5]
	s_cbranch_execz .LBB0_1055
	s_and_b32 s10, s16, 0xe0
	s_and_b32 s16, s16, 0xffffff00
	v_or_b32_e32 v37, s10, v33
	s_ashr_i32 s17, s16, 31
	v_lshl_add_u64 v[2:3], s[16:17], 2, v[26:27]
	v_lshlrev_b32_e32 v18, 2, v37
	v_lshl_add_u64 v[10:11], v[2:3], 0, v[18:19]
	global_load_dwordx4 v[2:5], v[10:11], off
	global_load_dwordx4 v[6:9], v[10:11], off offset:16
	ds_read2_b32 v[10:11], v35 offset1:1
	ds_read2_b32 v[12:13], v35 offset0:2 offset1:3
	ds_read2_b32 v[14:15], v35 offset0:4 offset1:5
	ds_read2_b32 v[16:17], v35 offset0:6 offset1:7
	v_add_u32_e32 v18, 0x1080, v35
	v_add_u32_e32 v38, 0x2100, v35
	v_add_u32_e32 v40, 0x3180, v35
	v_add_u32_e32 v42, 0x1088, v35
	v_add_u32_e32 v44, 0x2108, v35
	v_add_u32_e32 v46, 0x3188, v35
	v_add_u32_e32 v48, 0x1090, v35
	v_add_u32_e32 v50, 0x2110, v35
	v_add_u32_e32 v52, 0x3190, v35
	v_add_u32_e32 v54, 0x1098, v35
	v_add_u32_e32 v56, 0x2118, v35
	v_add_u32_e32 v58, 0x3198, v35
	s_waitcnt lgkmcnt(3)
	v_pk_add_f32 v[10:11], v[10:11], 0 op_sel_hi:[1,0]
	ds_read2_b32 v[30:31], v18 offset1:1
	ds_read2_b32 v[38:39], v38 offset1:1
	ds_read2_b32 v[40:41], v40 offset1:1
	ds_read2_b32 v[42:43], v42 offset1:1
	ds_read2_b32 v[44:45], v44 offset1:1
	ds_read2_b32 v[46:47], v46 offset1:1
	ds_read2_b32 v[48:49], v48 offset1:1
	ds_read2_b32 v[50:51], v50 offset1:1
	ds_read2_b32 v[52:53], v52 offset1:1
	ds_read2_b32 v[54:55], v54 offset1:1
	ds_read2_b32 v[56:57], v56 offset1:1
	ds_read2_b32 v[58:59], v58 offset1:1
	s_waitcnt lgkmcnt(14)
	v_pk_add_f32 v[12:13], v[12:13], 0 op_sel_hi:[1,0]
	s_waitcnt lgkmcnt(11)
	v_pk_add_f32 v[10:11], v[10:11], v[30:31]
	s_waitcnt lgkmcnt(8)
	v_pk_add_f32 v[12:13], v[12:13], v[42:43]
	v_pk_add_f32 v[10:11], v[10:11], v[38:39]
	v_pk_add_f32 v[14:15], v[14:15], 0 op_sel_hi:[1,0]
	s_waitcnt lgkmcnt(7)
	v_pk_add_f32 v[12:13], v[12:13], v[44:45]
	v_pk_add_f32 v[10:11], v[10:11], v[40:41]
	s_waitcnt lgkmcnt(5)
	v_pk_add_f32 v[14:15], v[14:15], v[48:49]
	v_pk_add_f32 v[12:13], v[12:13], v[46:47]
	v_pk_add_f32 v[16:17], v[16:17], 0 op_sel_hi:[1,0]
	s_waitcnt lgkmcnt(4)
	v_pk_add_f32 v[14:15], v[14:15], v[50:51]
	s_waitcnt lgkmcnt(2)
	v_pk_add_f32 v[16:17], v[16:17], v[54:55]
	v_pk_add_f32 v[14:15], v[14:15], v[52:53]
	s_waitcnt lgkmcnt(1)
	v_pk_add_f32 v[16:17], v[16:17], v[56:57]
	v_and_b32_e32 v60, 64, v36
	s_waitcnt lgkmcnt(0)
	v_pk_add_f32 v[16:17], v[16:17], v[58:59]
	v_xor_b32_e32 v61, 1, v36
	v_add_u32_e32 v18, 64, v60
	v_cmp_lt_i32_e32 vcc, v61, v18
	v_or_b32_e32 v60, s16, v37
	v_xor_b32_e32 v62, 2, v36
	v_cndmask_b32_e32 v37, v36, v61, vcc
	v_lshlrev_b32_e32 v37, 2, v37
	v_cmp_lt_i32_e32 vcc, v62, v18
	v_ashrrev_i32_e32 v61, 31, v60
	s_waitcnt vmcnt(1)
	v_pk_add_f32 v[2:3], v[10:11], v[2:3]
	v_pk_add_f32 v[10:11], v[12:13], v[4:5]
	v_pk_mul_f32 v[4:5], v[2:3], v[2:3]
	v_pk_mul_f32 v[12:13], v[10:11], v[10:11]
	v_add_f32_e32 v4, v4, v5
	s_waitcnt vmcnt(0)
	v_pk_add_f32 v[6:7], v[14:15], v[6:7]
	v_add_f32_e32 v4, v12, v4
	v_pk_mul_f32 v[14:15], v[6:7], v[6:7]
	v_add_f32_e32 v4, v13, v4
	v_pk_add_f32 v[8:9], v[16:17], v[8:9]
	v_add_f32_e32 v4, v14, v4
	v_pk_mul_f32 v[16:17], v[8:9], v[8:9]
	v_add_f32_e32 v4, v15, v4
	v_add_f32_e32 v4, v16, v4
	v_add_f32_e32 v12, v17, v4
	ds_bpermute_b32 v13, v37, v12
	v_cndmask_b32_e32 v14, v36, v62, vcc
	v_cvt_pk_bf16_f32 v4, v2, v3
	v_lshlrev_b32_e32 v3, 2, v14
	v_cvt_pk_bf16_f32 v5, v10, v11
	s_waitcnt lgkmcnt(0)
	v_add_f32_e32 v2, v12, v13
	ds_bpermute_b32 v3, v3, v2
	v_cvt_pk_bf16_f32 v6, v6, v7
	v_cvt_pk_bf16_f32 v7, v8, v9
	v_lshl_add_u64 v[8:9], v[60:61], 1, v[28:29]
	global_store_dwordx4 v[8:9], v[4:7], off
	s_and_b64 exec, exec, s[6:7]
	s_cbranch_execz .LBB0_1055
	s_waitcnt lgkmcnt(0)
	v_add_f32_e32 v2, v2, v3
	global_atomic_add_f32 v[24:25], v2, off
	s_branch .LBB0_1055

.LBB0_1155:
	s_or_b64 exec, exec, s[2:3]
	v_readlane_b32 s0, v255, 3
	v_readlane_b32 s1, v255, 4
	s_waitcnt lgkmcnt(0)
	s_barrier
	s_load_dwordx2 s[2:3], s[0:1], 0xd0
	v_mov_b32_e32 v2, v0
	s_lshr_b32 s0, s94, 1
	s_waitcnt lgkmcnt(0)
	s_add_u32 s12, s2, 0x10000
	s_addc_u32 s13, s3, 0
	s_add_u32 s36, s2, 0x3200000
	s_addc_u32 s37, s3, 0
	s_cmpk_gt_i32 s0, 0x7f
	v_readfirstlane_b32 s0, v2
	s_cbranch_scc1 .LBB0_1166
	s_ashr_i32 s6, s0, 6
	s_ashr_i32 s0, s0, 3
	s_movk_i32 s1, 0xffe0
	v_mov_b32_e32 v4, s0
	v_bfi_b32 v4, s1, v4, v2
	v_ashrrev_i32_e32 v5, 31, v4
	v_lshlrev_b64 v[4:5], 12, v[4:5]
	s_lshl_b32 s0, s6, 10
	v_bfe_u32 v3, v2, 5, 1
	v_lshl_add_u64 v[4:5], s[2:3], 0, v[4:5]
	s_and_b32 s10, s0, 0xc00
	s_mov_b32 s11, 0
	v_lshl_add_u64 v[4:5], v[4:5], 0, s[10:11]
	v_lshlrev_b32_e32 v18, 4, v3
	v_mov_b32_e32 v19, 0
	v_lshl_add_u64 v[4:5], v[4:5], 0, v[18:19]
	s_mov_b64 s[0:1], 0x9300000
	v_lshl_add_u64 v[20:21], v[4:5], 0, s[0:1]
	s_add_u32 s0, s36, s10
	s_addc_u32 s1, s37, 0
	v_lshl_add_u64 v[22:23], s[0:1], 0, v[18:19]
	s_lshl_b32 s0, s6, 5
	v_lshl_or_b32 v6, v3, 2, s0
	s_movk_i32 s0, 0x100
	v_and_b32_e32 v32, 31, v2
	v_lshrrev_b32_e32 v220, 7, v2
	s_and_b32 s66, s94, 1
	v_cmp_eq_u32_e64 s[6:7], s66, v220
	v_ashrrev_i32_e32 v3, 2, v2
	v_and_b32_e32 v4, 3, v2
	v_and_b32_e32 v2, 0x3fffff80, v2
	v_and_or_b32 v8, v3, 31, v2
	v_add_u32_e32 v2, 0x2000, v3
	v_ashrrev_i32_e32 v3, 31, v2
	v_lshl_add_u32 v9, v4, 5, 0
	v_lshlrev_b32_e32 v33, 3, v4
	v_lshlrev_b64 v[4:5], 12, v[2:3]
	s_movk_i32 s0, 0x84
	v_lshl_add_u32 v7, v32, 2, 0
	v_mul_lo_u32 v6, v6, s0
	v_mul_lo_u32 v8, v8, s0
	v_lshl_add_u64 v[26:27], s[2:3], 0, v[4:5]
	s_mov_b64 s[0:1], 0x5200000
	v_lshl_add_u64 v[24:25], v[2:3], 2, s[12:13]
	v_lshl_add_u64 v[28:29], v[26:27], 0, s[0:1]
	v_add_u32_e32 v34, v7, v6
	v_add_u32_e32 v35, v9, v8
	v_mov_b32_e32 v36, 0x358637bd
	s_mov_b32 s18, 0xf800000
	v_mov_b32_e32 v37, 0x260
	s_mov_b64 s[14:15], 0x93ff000
	s_lshr_b32 s19, s94, 1
	s_branch .LBB0_1159

.LBB0_1159:
	s_lshl_b32 s20, s19, 5
	v_or_b32_e32 v2, s20, v32
	v_ashrrev_i32_e32 v3, 31, v2
	v_lshlrev_b64 v[2:3], 12, v[2:3]
	v_lshl_add_u64 v[30:31], v[22:23], 0, v[2:3]
	s_mov_b64 s[0:1], -1
	s_mov_b32 s10, s11
	v_mov_b32_e32 v2, 0
	v_mov_b32_e32 v3, v19
	v_mov_b32_e32 v4, v19
	v_mov_b32_e32 v5, v19
	v_mov_b32_e32 v6, v19
	v_mov_b32_e32 v7, v19
	v_mov_b32_e32 v8, v19
	v_mov_b32_e32 v9, v19
	v_mov_b32_e32 v10, v19
	v_mov_b32_e32 v11, v19
	v_mov_b32_e32 v12, v19
	v_mov_b32_e32 v13, v19
	v_mov_b32_e32 v14, v19
	v_mov_b32_e32 v15, v19
	v_mov_b32_e32 v16, v19
	v_mov_b32_e32 v17, v19
	v_readfirstlane_b32 s66, v20
	v_readfirstlane_b32 s67, v21
	v_readfirstlane_b32 s68, v30
	v_readfirstlane_b32 s69, v31
	v_readfirstlane_b32 s70, v0
	v_mbcnt_lo_u32_b32 v220, -1, 0
	v_mbcnt_hi_u32_b32 v220, -1, v220
	s_lshr_b32 s70, s70, 6
	s_lshr_b32 s71, s70, 2
	s_and_b32 s74, s94, 1
	s_cmp_lg_u32 s71, s74
	s_cbranch_scc1 .Lsk3_end_2
	s_mul_i32 s70, s70, 9216
	s_add_i32 s70, s70, 36864
	v_lshrrev_b32_e32 v221, 3, v220
	v_and_b32_e32 v222, 7, v220
	v_lshlrev_b32_e32 v224, 12, v221
	v_lshl_add_u32 v224, v222, 4, v224
	v_mul_u32_u24_e32 v225, 144, v221
	v_lshl_add_u32 v225, v222, 4, v225
	v_add_u32_e32 v225, s70, v225
	v_and_b32_e32 v221, 31, v220
	v_lshrrev_b32_e32 v222, 5, v220
	v_mul_u32_u24_e32 v226, 144, v221
	v_lshl_add_u32 v226, v222, 4, v226
	v_add_u32_e32 v226, s70, v226
	s_add_u32 s72, s66, 0
	s_addc_u32 s73, s67, 0
	s_add_u32 s74, s68, 0
	s_addc_u32 s75, s69, 0
	global_load_dwordx4 v[106:109], v224, s[72:73]
	global_load_dwordx4 v[122:125], v224, s[74:75]
	s_add_u32 s72, s66, 32768
	s_addc_u32 s73, s67, 0
	s_add_u32 s74, s68, 32768
	s_addc_u32 s75, s69, 0
	global_load_dwordx4 v[110:113], v224, s[72:73]
	global_load_dwordx4 v[126:129], v224, s[74:75]
	s_add_u32 s72, s66, 65536
	s_addc_u32 s73, s67, 0
	s_add_u32 s74, s68, 65536
	s_addc_u32 s75, s69, 0
	global_load_dwordx4 v[114:117], v224, s[72:73]
	global_load_dwordx4 v[130:133], v224, s[74:75]
	s_add_u32 s72, s66, 98304
	s_addc_u32 s73, s67, 0
	s_add_u32 s74, s68, 98304
	s_addc_u32 s75, s69, 0
	global_load_dwordx4 v[118:121], v224, s[72:73]
	global_load_dwordx4 v[134:137], v224, s[74:75]
	s_add_u32 s72, s66, 128
	s_addc_u32 s73, s67, 0
	s_add_u32 s74, s68, 128
	s_addc_u32 s75, s69, 0
	global_load_dwordx4 v[138:141], v224, s[72:73]
	global_load_dwordx4 v[172:175], v224, s[74:75]
	s_add_u32 s72, s66, 32896
	s_addc_u32 s73, s67, 0
	s_add_u32 s74, s68, 32896
	s_addc_u32 s75, s69, 0
	global_load_dwordx4 v[142:145], v224, s[72:73]
	global_load_dwordx4 v[176:179], v224, s[74:75]
	s_add_u32 s72, s66, 65664
	s_addc_u32 s73, s67, 0
	s_add_u32 s74, s68, 65664
	s_addc_u32 s75, s69, 0
	global_load_dwordx4 v[146:149], v224, s[72:73]
	global_load_dwordx4 v[180:183], v224, s[74:75]
	s_add_u32 s72, s66, 98432
	s_addc_u32 s73, s67, 0
	s_add_u32 s74, s68, 98432
	s_addc_u32 s75, s69, 0
	global_load_dwordx4 v[168:171], v224, s[72:73]
	global_load_dwordx4 v[184:187], v224, s[74:75]
	s_add_u32 s72, s66, 256
	s_addc_u32 s73, s67, 0
	s_add_u32 s74, s68, 256
	s_addc_u32 s75, s69, 0
	global_load_dwordx4 v[188:191], v224, s[72:73]
	global_load_dwordx4 v[204:207], v224, s[74:75]
	s_add_u32 s72, s66, 33024
	s_addc_u32 s73, s67, 0
	s_add_u32 s74, s68, 33024
	s_addc_u32 s75, s69, 0
	global_load_dwordx4 v[192:195], v224, s[72:73]
	global_load_dwordx4 v[208:211], v224, s[74:75]
	s_add_u32 s72, s66, 65792
	s_addc_u32 s73, s67, 0
	s_add_u32 s74, s68, 65792
	s_addc_u32 s75, s69, 0
	global_load_dwordx4 v[196:199], v224, s[72:73]
	global_load_dwordx4 v[212:215], v224, s[74:75]
	s_add_u32 s72, s66, 98560
	s_addc_u32 s73, s67, 0
	s_add_u32 s74, s68, 98560
	s_addc_u32 s75, s69, 0
	global_load_dwordx4 v[200:203], v224, s[72:73]
	global_load_dwordx4 v[216:219], v224, s[74:75]
	s_add_u32 s72, s66, 384
	s_addc_u32 s73, s67, 0
	s_add_u32 s74, s68, 384
	s_addc_u32 s75, s69, 0
	global_load_dwordx4 v[228:231], v224, s[72:73]
	global_load_dwordx4 v[244:247], v224, s[74:75]
	s_add_u32 s72, s66, 33152
	s_addc_u32 s73, s67, 0
	s_add_u32 s74, s68, 33152
	s_addc_u32 s75, s69, 0
	global_load_dwordx4 v[232:235], v224, s[72:73]
	global_load_dwordx4 v[248:251], v224, s[74:75]
	s_add_u32 s72, s66, 65920
	s_addc_u32 s73, s67, 0
	s_add_u32 s74, s68, 65920
	s_addc_u32 s75, s69, 0
	global_load_dwordx4 v[236:239], v224, s[72:73]
	global_load_dwordx4 v[52:55], v224, s[74:75]
	s_add_u32 s72, s66, 98688
	s_addc_u32 s73, s67, 0
	s_add_u32 s74, s68, 98688
	s_addc_u32 s75, s69, 0
	global_load_dwordx4 v[240:243], v224, s[72:73]
	global_load_dwordx4 v[56:59], v224, s[74:75]
	s_waitcnt vmcnt(24)
	ds_write_b128 v225, v[106:109]
	ds_write_b128 v225, v[110:113] offset:1152
	ds_write_b128 v225, v[114:117] offset:2304
	ds_write_b128 v225, v[118:121] offset:3456
	ds_write_b128 v225, v[122:125] offset:4608
	ds_write_b128 v225, v[126:129] offset:5760
	ds_write_b128 v225, v[130:133] offset:6912
	ds_write_b128 v225, v[134:137] offset:8064
	s_nop 1
	s_add_u32 s72, s66, 512
	s_addc_u32 s73, s67, 0
	s_add_u32 s74, s68, 512
	s_addc_u32 s75, s69, 0
	global_load_dwordx4 v[106:109], v224, s[72:73]
	global_load_dwordx4 v[122:125], v224, s[74:75]
	s_add_u32 s72, s66, 33280
	s_addc_u32 s73, s67, 0
	s_add_u32 s74, s68, 33280
	s_addc_u32 s75, s69, 0
	global_load_dwordx4 v[110:113], v224, s[72:73]
	global_load_dwordx4 v[126:129], v224, s[74:75]
	s_add_u32 s72, s66, 66048
	s_addc_u32 s73, s67, 0
	s_add_u32 s74, s68, 66048
	s_addc_u32 s75, s69, 0
	global_load_dwordx4 v[114:117], v224, s[72:73]
	global_load_dwordx4 v[130:133], v224, s[74:75]
	s_add_u32 s72, s66, 98816
	s_addc_u32 s73, s67, 0
	s_add_u32 s74, s68, 98816
	s_addc_u32 s75, s69, 0
	global_load_dwordx4 v[118:121], v224, s[72:73]
	global_load_dwordx4 v[134:137], v224, s[74:75]
	s_waitcnt lgkmcnt(0)
	ds_read_b128 v[60:63], v226
	ds_read_b128 v[64:67], v226 offset:4608
	ds_read_b128 v[68:71], v226 offset:32
	ds_read_b128 v[80:83], v226 offset:4640
	ds_read_b128 v[88:91], v226 offset:64
	ds_read_b128 v[92:95], v226 offset:4672
	ds_read_b128 v[96:99], v226 offset:96
	ds_read_b128 v[100:103], v226 offset:4704
	s_waitcnt lgkmcnt(6)
	v_mfma_f32_32x32x16_bf16 v[2:17], v[60:63], v[64:67], v[2:17]
	s_waitcnt lgkmcnt(4)
	v_mfma_f32_32x32x16_bf16 v[2:17], v[68:71], v[80:83], v[2:17]
	s_waitcnt lgkmcnt(2)
	v_mfma_f32_32x32x16_bf16 v[2:17], v[88:91], v[92:95], v[2:17]
	s_waitcnt lgkmcnt(0)
	v_mfma_f32_32x32x16_bf16 v[2:17], v[96:99], v[100:103], v[2:17]
	s_waitcnt vmcnt(24)
	ds_write_b128 v225, v[138:141]
	ds_write_b128 v225, v[142:145] offset:1152
	ds_write_b128 v225, v[146:149] offset:2304
	ds_write_b128 v225, v[168:171] offset:3456
	ds_write_b128 v225, v[172:175] offset:4608
	ds_write_b128 v225, v[176:179] offset:5760
	ds_write_b128 v225, v[180:183] offset:6912
	ds_write_b128 v225, v[184:187] offset:8064
	s_nop 1
	s_add_u32 s72, s66, 640
	s_addc_u32 s73, s67, 0
	s_add_u32 s74, s68, 640
	s_addc_u32 s75, s69, 0
	global_load_dwordx4 v[138:141], v224, s[72:73]
	global_load_dwordx4 v[172:175], v224, s[74:75]
	s_add_u32 s72, s66, 33408
	s_addc_u32 s73, s67, 0
	s_add_u32 s74, s68, 33408
	s_addc_u32 s75, s69, 0
	global_load_dwordx4 v[142:145], v224, s[72:73]
	global_load_dwordx4 v[176:179], v224, s[74:75]
	s_add_u32 s72, s66, 66176
	s_addc_u32 s73, s67, 0
	s_add_u32 s74, s68, 66176
	s_addc_u32 s75, s69, 0
	global_load_dwordx4 v[146:149], v224, s[72:73]
	global_load_dwordx4 v[180:183], v224, s[74:75]
	s_add_u32 s72, s66, 98944
	s_addc_u32 s73, s67, 0
	s_add_u32 s74, s68, 98944
	s_addc_u32 s75, s69, 0
	global_load_dwordx4 v[168:171], v224, s[72:73]
	global_load_dwordx4 v[184:187], v224, s[74:75]
	s_waitcnt lgkmcnt(0)
	ds_read_b128 v[60:63], v226
	ds_read_b128 v[64:67], v226 offset:4608
	ds_read_b128 v[68:71], v226 offset:32
	ds_read_b128 v[80:83], v226 offset:4640
	ds_read_b128 v[88:91], v226 offset:64
	ds_read_b128 v[92:95], v226 offset:4672
	ds_read_b128 v[96:99], v226 offset:96
	ds_read_b128 v[100:103], v226 offset:4704
	s_waitcnt lgkmcnt(6)
	v_mfma_f32_32x32x16_bf16 v[2:17], v[60:63], v[64:67], v[2:17]
	s_waitcnt lgkmcnt(4)
	v_mfma_f32_32x32x16_bf16 v[2:17], v[68:71], v[80:83], v[2:17]
	s_waitcnt lgkmcnt(2)
	v_mfma_f32_32x32x16_bf16 v[2:17], v[88:91], v[92:95], v[2:17]
	s_waitcnt lgkmcnt(0)
	v_mfma_f32_32x32x16_bf16 v[2:17], v[96:99], v[100:103], v[2:17]
	s_waitcnt vmcnt(24)
	ds_write_b128 v225, v[188:191]
	ds_write_b128 v225, v[192:195] offset:1152
	ds_write_b128 v225, v[196:199] offset:2304
	ds_write_b128 v225, v[200:203] offset:3456
	ds_write_b128 v225, v[204:207] offset:4608
	ds_write_b128 v225, v[208:211] offset:5760
	ds_write_b128 v225, v[212:215] offset:6912
	ds_write_b128 v225, v[216:219] offset:8064
	s_nop 1
	s_add_u32 s72, s66, 768
	s_addc_u32 s73, s67, 0
	s_add_u32 s74, s68, 768
	s_addc_u32 s75, s69, 0
	global_load_dwordx4 v[188:191], v224, s[72:73]
	global_load_dwordx4 v[204:207], v224, s[74:75]
	s_add_u32 s72, s66, 33536
	s_addc_u32 s73, s67, 0
	s_add_u32 s74, s68, 33536
	s_addc_u32 s75, s69, 0
	global_load_dwordx4 v[192:195], v224, s[72:73]
	global_load_dwordx4 v[208:211], v224, s[74:75]
	s_add_u32 s72, s66, 66304
	s_addc_u32 s73, s67, 0
	s_add_u32 s74, s68, 66304
	s_addc_u32 s75, s69, 0
	global_load_dwordx4 v[196:199], v224, s[72:73]
	global_load_dwordx4 v[212:215], v224, s[74:75]
	s_add_u32 s72, s66, 99072
	s_addc_u32 s73, s67, 0
	s_add_u32 s74, s68, 99072
	s_addc_u32 s75, s69, 0
	global_load_dwordx4 v[200:203], v224, s[72:73]
	global_load_dwordx4 v[216:219], v224, s[74:75]
	s_waitcnt lgkmcnt(0)
	ds_read_b128 v[60:63], v226
	ds_read_b128 v[64:67], v226 offset:4608
	ds_read_b128 v[68:71], v226 offset:32
	ds_read_b128 v[80:83], v226 offset:4640
	ds_read_b128 v[88:91], v226 offset:64
	ds_read_b128 v[92:95], v226 offset:4672
	ds_read_b128 v[96:99], v226 offset:96
	ds_read_b128 v[100:103], v226 offset:4704
	s_waitcnt lgkmcnt(6)
	v_mfma_f32_32x32x16_bf16 v[2:17], v[60:63], v[64:67], v[2:17]
	s_waitcnt lgkmcnt(4)
	v_mfma_f32_32x32x16_bf16 v[2:17], v[68:71], v[80:83], v[2:17]
	s_waitcnt lgkmcnt(2)
	v_mfma_f32_32x32x16_bf16 v[2:17], v[88:91], v[92:95], v[2:17]
	s_waitcnt lgkmcnt(0)
	v_mfma_f32_32x32x16_bf16 v[2:17], v[96:99], v[100:103], v[2:17]
	s_waitcnt vmcnt(24)
	ds_write_b128 v225, v[228:231]
	ds_write_b128 v225, v[232:235] offset:1152
	ds_write_b128 v225, v[236:239] offset:2304
	ds_write_b128 v225, v[240:243] offset:3456
	ds_write_b128 v225, v[244:247] offset:4608
	ds_write_b128 v225, v[248:251] offset:5760
	ds_write_b128 v225, v[52:55] offset:6912
	ds_write_b128 v225, v[56:59] offset:8064
	s_nop 1
	s_add_u32 s72, s66, 896
	s_addc_u32 s73, s67, 0
	s_add_u32 s74, s68, 896
	s_addc_u32 s75, s69, 0
	global_load_dwordx4 v[228:231], v224, s[72:73]
	global_load_dwordx4 v[244:247], v224, s[74:75]
	s_add_u32 s72, s66, 33664
	s_addc_u32 s73, s67, 0
	s_add_u32 s74, s68, 33664
	s_addc_u32 s75, s69, 0
	global_load_dwordx4 v[232:235], v224, s[72:73]
	global_load_dwordx4 v[248:251], v224, s[74:75]
	s_add_u32 s72, s66, 66432
	s_addc_u32 s73, s67, 0
	s_add_u32 s74, s68, 66432
	s_addc_u32 s75, s69, 0
	global_load_dwordx4 v[236:239], v224, s[72:73]
	global_load_dwordx4 v[52:55], v224, s[74:75]
	s_add_u32 s72, s66, 99200
	s_addc_u32 s73, s67, 0
	s_add_u32 s74, s68, 99200
	s_addc_u32 s75, s69, 0
	global_load_dwordx4 v[240:243], v224, s[72:73]
	global_load_dwordx4 v[56:59], v224, s[74:75]
	s_waitcnt lgkmcnt(0)
	ds_read_b128 v[60:63], v226
	ds_read_b128 v[64:67], v226 offset:4608
	ds_read_b128 v[68:71], v226 offset:32
	ds_read_b128 v[80:83], v226 offset:4640
	ds_read_b128 v[88:91], v226 offset:64
	ds_read_b128 v[92:95], v226 offset:4672
	ds_read_b128 v[96:99], v226 offset:96
	ds_read_b128 v[100:103], v226 offset:4704
	s_waitcnt lgkmcnt(6)
	v_mfma_f32_32x32x16_bf16 v[2:17], v[60:63], v[64:67], v[2:17]
	s_waitcnt lgkmcnt(4)
	v_mfma_f32_32x32x16_bf16 v[2:17], v[68:71], v[80:83], v[2:17]
	s_waitcnt lgkmcnt(2)
	v_mfma_f32_32x32x16_bf16 v[2:17], v[88:91], v[92:95], v[2:17]
	s_waitcnt lgkmcnt(0)
	v_mfma_f32_32x32x16_bf16 v[2:17], v[96:99], v[100:103], v[2:17]
	s_waitcnt vmcnt(24)
	ds_write_b128 v225, v[106:109]
	ds_write_b128 v225, v[110:113] offset:1152
	ds_write_b128 v225, v[114:117] offset:2304
	ds_write_b128 v225, v[118:121] offset:3456
	ds_write_b128 v225, v[122:125] offset:4608
	ds_write_b128 v225, v[126:129] offset:5760
	ds_write_b128 v225, v[130:133] offset:6912
	ds_write_b128 v225, v[134:137] offset:8064
	s_waitcnt lgkmcnt(0)
	ds_read_b128 v[60:63], v226
	ds_read_b128 v[64:67], v226 offset:4608
	ds_read_b128 v[68:71], v226 offset:32
	ds_read_b128 v[80:83], v226 offset:4640
	ds_read_b128 v[88:91], v226 offset:64
	ds_read_b128 v[92:95], v226 offset:4672
	ds_read_b128 v[96:99], v226 offset:96
	ds_read_b128 v[100:103], v226 offset:4704
	s_waitcnt lgkmcnt(6)
	v_mfma_f32_32x32x16_bf16 v[2:17], v[60:63], v[64:67], v[2:17]
	s_waitcnt lgkmcnt(4)
	v_mfma_f32_32x32x16_bf16 v[2:17], v[68:71], v[80:83], v[2:17]
	s_waitcnt lgkmcnt(2)
	v_mfma_f32_32x32x16_bf16 v[2:17], v[88:91], v[92:95], v[2:17]
	s_waitcnt lgkmcnt(0)
	v_mfma_f32_32x32x16_bf16 v[2:17], v[96:99], v[100:103], v[2:17]
	s_waitcnt vmcnt(16)
	ds_write_b128 v225, v[138:141]
	ds_write_b128 v225, v[142:145] offset:1152
	ds_write_b128 v225, v[146:149] offset:2304
	ds_write_b128 v225, v[168:171] offset:3456
	ds_write_b128 v225, v[172:175] offset:4608
	ds_write_b128 v225, v[176:179] offset:5760
	ds_write_b128 v225, v[180:183] offset:6912
	ds_write_b128 v225, v[184:187] offset:8064
	s_waitcnt lgkmcnt(0)
	ds_read_b128 v[60:63], v226
	ds_read_b128 v[64:67], v226 offset:4608
	ds_read_b128 v[68:71], v226 offset:32
	ds_read_b128 v[80:83], v226 offset:4640
	ds_read_b128 v[88:91], v226 offset:64
	ds_read_b128 v[92:95], v226 offset:4672
	ds_read_b128 v[96:99], v226 offset:96
	ds_read_b128 v[100:103], v226 offset:4704
	s_waitcnt lgkmcnt(6)
	v_mfma_f32_32x32x16_bf16 v[2:17], v[60:63], v[64:67], v[2:17]
	s_waitcnt lgkmcnt(4)
	v_mfma_f32_32x32x16_bf16 v[2:17], v[68:71], v[80:83], v[2:17]
	s_waitcnt lgkmcnt(2)
	v_mfma_f32_32x32x16_bf16 v[2:17], v[88:91], v[92:95], v[2:17]
	s_waitcnt lgkmcnt(0)
	v_mfma_f32_32x32x16_bf16 v[2:17], v[96:99], v[100:103], v[2:17]
	s_waitcnt vmcnt(8)
	ds_write_b128 v225, v[188:191]
	ds_write_b128 v225, v[192:195] offset:1152
	ds_write_b128 v225, v[196:199] offset:2304
	ds_write_b128 v225, v[200:203] offset:3456
	ds_write_b128 v225, v[204:207] offset:4608
	ds_write_b128 v225, v[208:211] offset:5760
	ds_write_b128 v225, v[212:215] offset:6912
	ds_write_b128 v225, v[216:219] offset:8064
	s_waitcnt lgkmcnt(0)
	ds_read_b128 v[60:63], v226
	ds_read_b128 v[64:67], v226 offset:4608
	ds_read_b128 v[68:71], v226 offset:32
	ds_read_b128 v[80:83], v226 offset:4640
	ds_read_b128 v[88:91], v226 offset:64
	ds_read_b128 v[92:95], v226 offset:4672
	ds_read_b128 v[96:99], v226 offset:96
	ds_read_b128 v[100:103], v226 offset:4704
	s_waitcnt lgkmcnt(6)
	v_mfma_f32_32x32x16_bf16 v[2:17], v[60:63], v[64:67], v[2:17]
	s_waitcnt lgkmcnt(4)
	v_mfma_f32_32x32x16_bf16 v[2:17], v[68:71], v[80:83], v[2:17]
	s_waitcnt lgkmcnt(2)
	v_mfma_f32_32x32x16_bf16 v[2:17], v[88:91], v[92:95], v[2:17]
	s_waitcnt lgkmcnt(0)
	v_mfma_f32_32x32x16_bf16 v[2:17], v[96:99], v[100:103], v[2:17]
	s_waitcnt vmcnt(0)
	ds_write_b128 v225, v[228:231]
	ds_write_b128 v225, v[232:235] offset:1152
	ds_write_b128 v225, v[236:239] offset:2304
	ds_write_b128 v225, v[240:243] offset:3456
	ds_write_b128 v225, v[244:247] offset:4608
	ds_write_b128 v225, v[248:251] offset:5760
	ds_write_b128 v225, v[52:55] offset:6912
	ds_write_b128 v225, v[56:59] offset:8064
	s_waitcnt lgkmcnt(0)
	ds_read_b128 v[60:63], v226
	ds_read_b128 v[64:67], v226 offset:4608
	ds_read_b128 v[68:71], v226 offset:32
	ds_read_b128 v[80:83], v226 offset:4640
	ds_read_b128 v[88:91], v226 offset:64
	ds_read_b128 v[92:95], v226 offset:4672
	ds_read_b128 v[96:99], v226 offset:96
	ds_read_b128 v[100:103], v226 offset:4704
	s_waitcnt lgkmcnt(6)
	v_mfma_f32_32x32x16_bf16 v[2:17], v[60:63], v[64:67], v[2:17]
	s_waitcnt lgkmcnt(4)
	v_mfma_f32_32x32x16_bf16 v[2:17], v[68:71], v[80:83], v[2:17]
	s_waitcnt lgkmcnt(2)
	v_mfma_f32_32x32x16_bf16 v[2:17], v[88:91], v[92:95], v[2:17]
	s_waitcnt lgkmcnt(0)
	v_mfma_f32_32x32x16_bf16 v[2:17], v[96:99], v[100:103], v[2:17]
.Lsk3_end_2:
	s_mov_b32 s8, 0x200
	s_mov_b32 s9, 0
	v_lshl_add_u64 v[58:59], v[20:21], 0, s[8:9]
	v_lshl_add_u64 v[60:61], v[30:31], 0, s[8:9]
	s_movk_i32 s10, 0x100
	s_mov_b64 s[0:1], 0
	s_mov_b64 vcc, exec
	s_nop 10
	ds_write2_b32 v34, v2, v3 offset1:33
	ds_write2_b32 v34, v4, v5 offset0:66 offset1:99
	v_add_u32_e32 v2, 0x400, v34
	ds_write2_b32 v2, v6, v7 offset0:8 offset1:41
	ds_write2_b32 v2, v8, v9 offset0:74 offset1:107
	v_add_u32_e32 v2, 0x800, v34
	ds_write2_b32 v2, v10, v11 offset0:16 offset1:49
	ds_write2_b32 v2, v12, v13 offset0:82 offset1:115
	v_add_u32_e32 v2, 0xc00, v34
	ds_write2_b32 v2, v14, v15 offset0:24 offset1:57
	ds_write2_b32 v2, v16, v17 offset0:90 offset1:123
	s_waitcnt lgkmcnt(0)
	s_barrier
	s_and_saveexec_b64 s[0:1], s[6:7]
	s_cbranch_execz .LBB0_1158
	global_load_dword v18, v[24:25], off
	ds_read2_b32 v[2:3], v35 offset1:1
	ds_read2_b32 v[4:5], v35 offset0:2 offset1:3
	ds_read2_b32 v[6:7], v35 offset0:4 offset1:5
	ds_read2_b32 v[8:9], v35 offset0:6 offset1:7
	v_add_u32_e32 v10, 0x1080, v35
	v_add_u32_e32 v12, 0x2100, v35
	v_add_u32_e32 v14, 0x3180, v35
	v_add_u32_e32 v16, 0x1088, v35
	v_add_u32_e32 v30, 0x2108, v35
	v_add_u32_e32 v38, 0x3188, v35
	v_add_u32_e32 v40, 0x1090, v35
	v_add_u32_e32 v42, 0x2110, v35
	v_add_u32_e32 v44, 0x3190, v35
	v_add_u32_e32 v46, 0x1098, v35
	v_add_u32_e32 v48, 0x2118, v35
	v_add_u32_e32 v50, 0x3198, v35
	ds_read2_b32 v[10:11], v10 offset1:1
	ds_read2_b32 v[12:13], v12 offset1:1
	ds_read2_b32 v[14:15], v14 offset1:1
	ds_read2_b32 v[16:17], v16 offset1:1
	ds_read2_b32 v[30:31], v30 offset1:1
	ds_read2_b32 v[38:39], v38 offset1:1
	ds_read2_b32 v[40:41], v40 offset1:1
	ds_read2_b32 v[42:43], v42 offset1:1
	ds_read2_b32 v[44:45], v44 offset1:1
	ds_read2_b32 v[46:47], v46 offset1:1
	ds_read2_b32 v[48:49], v48 offset1:1
	ds_read2_b32 v[50:51], v50 offset1:1
	s_waitcnt lgkmcnt(14)
	v_add_f32_e32 v52, 0, v2
	v_add_f32_e32 v53, 0, v3
	v_pk_add_f32 v[2:3], v[4:5], 0 op_sel_hi:[1,0]
	s_waitcnt lgkmcnt(13)
	v_pk_add_f32 v[4:5], v[6:7], 0 op_sel_hi:[1,0]
	s_waitcnt lgkmcnt(12)
	v_pk_add_f32 v[6:7], v[8:9], 0 op_sel_hi:[1,0]
	s_waitcnt lgkmcnt(11)
	v_add_f32_e32 v8, v52, v10
	s_waitcnt lgkmcnt(2)
	v_pk_add_f32 v[6:7], v[6:7], v[46:47]
	v_add_f32_e32 v9, v53, v11
	s_waitcnt lgkmcnt(1)
	v_pk_add_f32 v[10:11], v[6:7], v[48:49]
	v_add_f32_e32 v8, v8, v12
	v_add_f32_e32 v9, v9, v13
	v_add_f32_e32 v13, v8, v14
	v_pk_add_f32 v[2:3], v[2:3], v[16:17]
	v_pk_add_f32 v[4:5], v[4:5], v[40:41]
	v_pk_add_f32 v[2:3], v[2:3], v[30:31]
	v_pk_add_f32 v[4:5], v[4:5], v[42:43]
	v_add_f32_e32 v15, v9, v15
	v_pk_add_f32 v[8:9], v[4:5], v[44:45]
	s_ashr_i32 s21, s19, 3
	s_mov_b64 s[16:17], -1
	s_cmp_lt_i32 s21, 8
	s_waitcnt lgkmcnt(0)
	v_pk_add_f32 v[10:11], v[10:11], v[50:51]
	s_waitcnt vmcnt(0)
	v_fmamk_f32 v6, v18, 0x3a000000, v36
	v_mul_f32_e32 v7, 0x4f800000, v6
	v_cmp_gt_f32_e32 vcc, s18, v6
	s_nop 1
	v_cndmask_b32_e32 v12, v6, v7, vcc
	v_sqrt_f32_e32 v14, v12
	v_pk_add_f32 v[6:7], v[2:3], v[38:39]
	v_add_u32_e32 v2, -1, v14
	v_add_u32_e32 v3, 1, v14
	v_fma_f32 v4, -v2, v14, v12
	v_fma_f32 v5, -v3, v14, v12
	v_cmp_ge_f32_e64 s[8:9], 0, v4
	s_nop 1
	v_cndmask_b32_e64 v2, v14, v2, s[8:9]
	v_cmp_lt_f32_e64 s[8:9], 0, v5
	s_nop 1
	v_cndmask_b32_e64 v2, v2, v3, s[8:9]
	v_mul_f32_e32 v3, 0x37800000, v2
	v_cndmask_b32_e32 v2, v2, v3, vcc
	v_cmp_class_f32_e32 vcc, v12, v37
	s_nop 1
	v_cndmask_b32_e32 v2, v2, v12, vcc
	v_div_scale_f32 v3, s[8:9], v2, v2, 1.0
	v_rcp_f32_e32 v4, v3
	v_div_scale_f32 v5, vcc, 1.0, v2, 1.0
	v_fma_f32 v12, -v3, v4, 1.0
	v_fmac_f32_e32 v4, v12, v4
	v_mul_f32_e32 v12, v5, v4
	v_fma_f32 v14, -v3, v12, v5
	v_fmac_f32_e32 v12, v14, v4
	v_fma_f32 v3, -v3, v12, v5
	v_div_fmas_f32 v3, v3, v4, v12
	v_div_fixup_f32 v12, v3, v2, 1.0
	v_mul_f32_e32 v14, v13, v12
	v_mul_f32_e32 v15, v15, v12
	s_cbranch_scc1 .LBB0_1164
	v_pk_mul_f32 v[4:5], v[6:7], v[12:13] op_sel_hi:[1,0]
	v_mul_f32_e32 v2, 0xbfb8aa3b, v14
	v_mul_f32_e32 v13, 0xbfb8aa3b, v4
	v_exp_f32_e32 v13, v13
	v_mul_f32_e32 v16, 0xbfb8aa3b, v5
	v_exp_f32_e32 v17, v16
	v_mul_f32_e32 v3, 0xbfb8aa3b, v15
	v_add_f32_e32 v13, 1.0, v13
	v_rcp_f32_e32 v16, v13
	v_add_f32_e32 v13, 1.0, v17
	v_pk_mul_f32 v[30:31], v[8:9], v[12:13] op_sel_hi:[1,0]
	v_exp_f32_e32 v2, v2
	v_mul_f32_e32 v17, 0xbfb8aa3b, v30
	v_exp_f32_e32 v18, v17
	v_mul_f32_e32 v17, 0xbfb8aa3b, v31
	v_exp_f32_e32 v39, v17
	v_rcp_f32_e32 v17, v13
	v_add_f32_e32 v13, 1.0, v18
	v_rcp_f32_e32 v38, v13
	v_add_f32_e32 v13, 1.0, v39
	v_pk_mul_f32 v[40:41], v[10:11], v[12:13] op_sel_hi:[1,0]
	v_exp_f32_e32 v3, v3
	v_mul_f32_e32 v18, 0xbfb8aa3b, v40
	v_exp_f32_e32 v18, v18
	v_mul_f32_e32 v39, 0xbfb8aa3b, v41
	v_exp_f32_e32 v43, v39
	v_add_f32_e32 v2, 1.0, v2
	v_add_f32_e32 v3, 1.0, v3
	v_rcp_f32_e32 v39, v13
	v_add_f32_e32 v13, 1.0, v18
	v_rcp_f32_e32 v2, v2
	v_rcp_f32_e32 v3, v3
	v_rcp_f32_e32 v42, v13
	v_add_f32_e32 v13, 1.0, v43
	v_rcp_f32_e32 v43, v13
	v_pk_mul_f32 v[2:3], v[14:15], v[2:3]
	v_pk_mul_f32 v[4:5], v[4:5], v[16:17]
	v_pk_mul_f32 v[16:17], v[30:31], v[38:39]
	s_lshl_b32 s10, s21, 9
	v_pk_mul_f32 v[30:31], v[40:41], v[42:43]
	v_cvt_pk_bf16_f32 v2, v2, v3
	v_cvt_pk_bf16_f32 v3, v4, v5
	v_cvt_pk_bf16_f32 v4, v16, v17
	v_lshl_add_u64 v[16:17], v[26:27], 0, s[10:11]
	v_cvt_pk_bf16_f32 v5, v30, v31
	v_lshl_add_u64 v[16:17], v[16:17], 0, s[14:15]
	s_mov_b64 s[16:17], 0

.LBB0_1466:
	s_or_b64 exec, exec, s[0:1]
	v_readlane_b32 s2, v255, 3
	v_readlane_b32 s3, v255, 4
	s_waitcnt lgkmcnt(0)
	s_barrier
	s_load_dwordx2 s[8:9], s[2:3], 0xd0
	s_load_dwordx2 s[0:1], s[2:3], 0xb0
	v_mov_b32_e32 v2, v0
	v_cndmask_b32_e64 v3, 0, 1, s[50:51]
	s_waitcnt lgkmcnt(0)
	s_add_u32 s2, s8, 0xd600000
	s_addc_u32 s3, s9, 0
	s_add_u32 s10, s8, 0x9400000
	s_addc_u32 s11, s9, 0
	s_add_u32 s12, s8, 0xb500000
	s_addc_u32 s13, s9, 0
	s_add_u32 s38, s8, 0x4200000
	s_addc_u32 s39, s9, 0
	v_cmp_ne_u32_e64 s[6:7], 1, v3
	s_andn2_b64 vcc, exec, s[50:51]
	v_readfirstlane_b32 s14, v2
	s_cbranch_vccnz .LBB0_1473
	s_ashr_i32 s16, s14, 6
	s_ashr_i32 s14, s14, 3
	s_movk_i32 s15, 0xffe0
	v_mov_b32_e32 v4, s14
	v_bfi_b32 v4, s15, v4, v2
	v_ashrrev_i32_e32 v5, 31, v4
	v_lshlrev_b64 v[4:5], 12, v[4:5]
	v_lshl_add_u64 v[4:5], s[8:9], 0, v[4:5]
	s_lshl_b32 s8, s16, 10
	v_bfe_u32 v3, v2, 5, 1
	s_and_b32 s14, s8, 0xc00
	s_mov_b32 s15, 0
	v_lshl_add_u64 v[4:5], v[4:5], 0, s[14:15]
	v_lshlrev_b32_e32 v18, 4, v3
	v_mov_b32_e32 v19, 0
	v_lshl_add_u64 v[4:5], v[4:5], 0, v[18:19]
	s_mov_b64 s[8:9], 0xf600000
	v_lshl_add_u64 v[20:21], v[4:5], 0, s[8:9]
	s_add_u32 s8, s38, s14
	s_addc_u32 s9, s39, 0
	v_lshl_add_u64 v[22:23], s[8:9], 0, v[18:19]
	s_lshl_b32 s8, s16, 5
	v_lshl_or_b32 v4, v3, 2, s8
	s_movk_i32 s8, 0x100
	v_and_b32_e32 v30, 31, v2
	v_lshrrev_b32_e32 v220, 7, v2
	s_and_b32 s66, s94, 1
	v_cmp_eq_u32_e64 s[8:9], s66, v220
	v_ashrrev_i32_e32 v3, 2, v2
	v_and_b32_e32 v6, 3, v2
	v_and_b32_e32 v2, 0x3fffff80, v2
	v_and_or_b32 v7, v3, 31, v2
	v_add_u32_e32 v2, 0x2000, v3
	v_ashrrev_i32_e32 v3, 31, v2
	s_movk_i32 s14, 0x84
	v_lshl_add_u32 v5, v30, 2, 0
	v_lshl_add_u32 v8, v6, 5, 0
	v_lshlrev_b32_e32 v31, 3, v6
	v_lshlrev_b64 v[24:25], 11, v[2:3]
	v_lshlrev_b64 v[2:3], 12, v[2:3]
	v_mul_lo_u32 v4, v4, s14
	v_mul_lo_u32 v6, v7, s14
	v_lshl_add_u64 v[26:27], s[12:13], 0, v[2:3]
	v_add_u32_e32 v32, v5, v4
	v_add_u32_e32 v33, v8, v6
	s_lshr_b32 s20, s94, 1
	s_branch .LBB0_1469

.LBB0_1469:
	s_lshl_b32 s18, s20, 5
	v_or_b32_e32 v2, s18, v30
	v_ashrrev_i32_e32 v3, 31, v2
	v_lshlrev_b64 v[2:3], 12, v[2:3]
	v_lshl_add_u64 v[28:29], v[22:23], 0, v[2:3]
	s_mov_b64 s[16:17], -1
	s_mov_b32 s14, s15
	v_mov_b32_e32 v2, 0
	v_mov_b32_e32 v3, v19
	v_mov_b32_e32 v4, v19
	v_mov_b32_e32 v5, v19
	v_mov_b32_e32 v6, v19
	v_mov_b32_e32 v7, v19
	v_mov_b32_e32 v8, v19
	v_mov_b32_e32 v9, v19
	v_mov_b32_e32 v10, v19
	v_mov_b32_e32 v11, v19
	v_mov_b32_e32 v12, v19
	v_mov_b32_e32 v13, v19
	v_mov_b32_e32 v14, v19
	v_mov_b32_e32 v15, v19
	v_mov_b32_e32 v16, v19
	v_mov_b32_e32 v17, v19
	v_readfirstlane_b32 s66, v20
	v_readfirstlane_b32 s67, v21
	v_readfirstlane_b32 s68, v28
	v_readfirstlane_b32 s69, v29
	v_readfirstlane_b32 s70, v0
	v_mbcnt_lo_u32_b32 v220, -1, 0
	v_mbcnt_hi_u32_b32 v220, -1, v220
	s_lshr_b32 s70, s70, 6
	s_lshr_b32 s71, s70, 2
	s_and_b32 s74, s94, 1
	s_cmp_lg_u32 s71, s74
	s_cbranch_scc1 .Lsk3_end_3
	s_mul_i32 s70, s70, 9216
	s_add_i32 s70, s70, 36864
	v_lshrrev_b32_e32 v221, 3, v220
	v_and_b32_e32 v222, 7, v220
	v_lshlrev_b32_e32 v224, 12, v221
	v_lshl_add_u32 v224, v222, 4, v224
	v_mul_u32_u24_e32 v225, 144, v221
	v_lshl_add_u32 v225, v222, 4, v225
	v_add_u32_e32 v225, s70, v225
	v_and_b32_e32 v221, 31, v220
	v_lshrrev_b32_e32 v222, 5, v220
	v_mul_u32_u24_e32 v226, 144, v221
	v_lshl_add_u32 v226, v222, 4, v226
	v_add_u32_e32 v226, s70, v226
	s_add_u32 s72, s66, 0
	s_addc_u32 s73, s67, 0
	s_add_u32 s74, s68, 0
	s_addc_u32 s75, s69, 0
	global_load_dwordx4 v[106:109], v224, s[72:73]
	global_load_dwordx4 v[122:125], v224, s[74:75]
	s_add_u32 s72, s66, 32768
	s_addc_u32 s73, s67, 0
	s_add_u32 s74, s68, 32768
	s_addc_u32 s75, s69, 0
	global_load_dwordx4 v[110:113], v224, s[72:73]
	global_load_dwordx4 v[126:129], v224, s[74:75]
	s_add_u32 s72, s66, 65536
	s_addc_u32 s73, s67, 0
	s_add_u32 s74, s68, 65536
	s_addc_u32 s75, s69, 0
	global_load_dwordx4 v[114:117], v224, s[72:73]
	global_load_dwordx4 v[130:133], v224, s[74:75]
	s_add_u32 s72, s66, 98304
	s_addc_u32 s73, s67, 0
	s_add_u32 s74, s68, 98304
	s_addc_u32 s75, s69, 0
	global_load_dwordx4 v[118:121], v224, s[72:73]
	global_load_dwordx4 v[134:137], v224, s[74:75]
	s_add_u32 s72, s66, 128
	s_addc_u32 s73, s67, 0
	s_add_u32 s74, s68, 128
	s_addc_u32 s75, s69, 0
	global_load_dwordx4 v[138:141], v224, s[72:73]
	global_load_dwordx4 v[172:175], v224, s[74:75]
	s_add_u32 s72, s66, 32896
	s_addc_u32 s73, s67, 0
	s_add_u32 s74, s68, 32896
	s_addc_u32 s75, s69, 0
	global_load_dwordx4 v[142:145], v224, s[72:73]
	global_load_dwordx4 v[176:179], v224, s[74:75]
	s_add_u32 s72, s66, 65664
	s_addc_u32 s73, s67, 0
	s_add_u32 s74, s68, 65664
	s_addc_u32 s75, s69, 0
	global_load_dwordx4 v[146:149], v224, s[72:73]
	global_load_dwordx4 v[180:183], v224, s[74:75]
	s_add_u32 s72, s66, 98432
	s_addc_u32 s73, s67, 0
	s_add_u32 s74, s68, 98432
	s_addc_u32 s75, s69, 0
	global_load_dwordx4 v[168:171], v224, s[72:73]
	global_load_dwordx4 v[184:187], v224, s[74:75]
	s_add_u32 s72, s66, 256
	s_addc_u32 s73, s67, 0
	s_add_u32 s74, s68, 256
	s_addc_u32 s75, s69, 0
	global_load_dwordx4 v[188:191], v224, s[72:73]
	global_load_dwordx4 v[204:207], v224, s[74:75]
	s_add_u32 s72, s66, 33024
	s_addc_u32 s73, s67, 0
	s_add_u32 s74, s68, 33024
	s_addc_u32 s75, s69, 0
	global_load_dwordx4 v[192:195], v224, s[72:73]
	global_load_dwordx4 v[208:211], v224, s[74:75]
	s_add_u32 s72, s66, 65792
	s_addc_u32 s73, s67, 0
	s_add_u32 s74, s68, 65792
	s_addc_u32 s75, s69, 0
	global_load_dwordx4 v[196:199], v224, s[72:73]
	global_load_dwordx4 v[212:215], v224, s[74:75]
	s_add_u32 s72, s66, 98560
	s_addc_u32 s73, s67, 0
	s_add_u32 s74, s68, 98560
	s_addc_u32 s75, s69, 0
	global_load_dwordx4 v[200:203], v224, s[72:73]
	global_load_dwordx4 v[216:219], v224, s[74:75]
	s_add_u32 s72, s66, 384
	s_addc_u32 s73, s67, 0
	s_add_u32 s74, s68, 384
	s_addc_u32 s75, s69, 0
	global_load_dwordx4 v[228:231], v224, s[72:73]
	global_load_dwordx4 v[244:247], v224, s[74:75]
	s_add_u32 s72, s66, 33152
	s_addc_u32 s73, s67, 0
	s_add_u32 s74, s68, 33152
	s_addc_u32 s75, s69, 0
	global_load_dwordx4 v[232:235], v224, s[72:73]
	global_load_dwordx4 v[248:251], v224, s[74:75]
	s_add_u32 s72, s66, 65920
	s_addc_u32 s73, s67, 0
	s_add_u32 s74, s68, 65920
	s_addc_u32 s75, s69, 0
	global_load_dwordx4 v[236:239], v224, s[72:73]
	global_load_dwordx4 v[52:55], v224, s[74:75]
	s_add_u32 s72, s66, 98688
	s_addc_u32 s73, s67, 0
	s_add_u32 s74, s68, 98688
	s_addc_u32 s75, s69, 0
	global_load_dwordx4 v[240:243], v224, s[72:73]
	global_load_dwordx4 v[56:59], v224, s[74:75]
	s_waitcnt vmcnt(24)
	ds_write_b128 v225, v[106:109]
	ds_write_b128 v225, v[110:113] offset:1152
	ds_write_b128 v225, v[114:117] offset:2304
	ds_write_b128 v225, v[118:121] offset:3456
	ds_write_b128 v225, v[122:125] offset:4608
	ds_write_b128 v225, v[126:129] offset:5760
	ds_write_b128 v225, v[130:133] offset:6912
	ds_write_b128 v225, v[134:137] offset:8064
	s_nop 1
	s_add_u32 s72, s66, 512
	s_addc_u32 s73, s67, 0
	s_add_u32 s74, s68, 512
	s_addc_u32 s75, s69, 0
	global_load_dwordx4 v[106:109], v224, s[72:73]
	global_load_dwordx4 v[122:125], v224, s[74:75]
	s_add_u32 s72, s66, 33280
	s_addc_u32 s73, s67, 0
	s_add_u32 s74, s68, 33280
	s_addc_u32 s75, s69, 0
	global_load_dwordx4 v[110:113], v224, s[72:73]
	global_load_dwordx4 v[126:129], v224, s[74:75]
	s_add_u32 s72, s66, 66048
	s_addc_u32 s73, s67, 0
	s_add_u32 s74, s68, 66048
	s_addc_u32 s75, s69, 0
	global_load_dwordx4 v[114:117], v224, s[72:73]
	global_load_dwordx4 v[130:133], v224, s[74:75]
	s_add_u32 s72, s66, 98816
	s_addc_u32 s73, s67, 0
	s_add_u32 s74, s68, 98816
	s_addc_u32 s75, s69, 0
	global_load_dwordx4 v[118:121], v224, s[72:73]
	global_load_dwordx4 v[134:137], v224, s[74:75]
	s_waitcnt lgkmcnt(0)
	ds_read_b128 v[60:63], v226
	ds_read_b128 v[64:67], v226 offset:4608
	ds_read_b128 v[68:71], v226 offset:32
	ds_read_b128 v[80:83], v226 offset:4640
	ds_read_b128 v[88:91], v226 offset:64
	ds_read_b128 v[92:95], v226 offset:4672
	ds_read_b128 v[96:99], v226 offset:96
	ds_read_b128 v[100:103], v226 offset:4704
	s_waitcnt lgkmcnt(6)
	v_mfma_f32_32x32x16_bf16 v[2:17], v[60:63], v[64:67], v[2:17]
	s_waitcnt lgkmcnt(4)
	v_mfma_f32_32x32x16_bf16 v[2:17], v[68:71], v[80:83], v[2:17]
	s_waitcnt lgkmcnt(2)
	v_mfma_f32_32x32x16_bf16 v[2:17], v[88:91], v[92:95], v[2:17]
	s_waitcnt lgkmcnt(0)
	v_mfma_f32_32x32x16_bf16 v[2:17], v[96:99], v[100:103], v[2:17]
	s_waitcnt vmcnt(24)
	ds_write_b128 v225, v[138:141]
	ds_write_b128 v225, v[142:145] offset:1152
	ds_write_b128 v225, v[146:149] offset:2304
	ds_write_b128 v225, v[168:171] offset:3456
	ds_write_b128 v225, v[172:175] offset:4608
	ds_write_b128 v225, v[176:179] offset:5760
	ds_write_b128 v225, v[180:183] offset:6912
	ds_write_b128 v225, v[184:187] offset:8064
	s_nop 1
	s_add_u32 s72, s66, 640
	s_addc_u32 s73, s67, 0
	s_add_u32 s74, s68, 640
	s_addc_u32 s75, s69, 0
	global_load_dwordx4 v[138:141], v224, s[72:73]
	global_load_dwordx4 v[172:175], v224, s[74:75]
	s_add_u32 s72, s66, 33408
	s_addc_u32 s73, s67, 0
	s_add_u32 s74, s68, 33408
	s_addc_u32 s75, s69, 0
	global_load_dwordx4 v[142:145], v224, s[72:73]
	global_load_dwordx4 v[176:179], v224, s[74:75]
	s_add_u32 s72, s66, 66176
	s_addc_u32 s73, s67, 0
	s_add_u32 s74, s68, 66176
	s_addc_u32 s75, s69, 0
	global_load_dwordx4 v[146:149], v224, s[72:73]
	global_load_dwordx4 v[180:183], v224, s[74:75]
	s_add_u32 s72, s66, 98944
	s_addc_u32 s73, s67, 0
	s_add_u32 s74, s68, 98944
	s_addc_u32 s75, s69, 0
	global_load_dwordx4 v[168:171], v224, s[72:73]
	global_load_dwordx4 v[184:187], v224, s[74:75]
	s_waitcnt lgkmcnt(0)
	ds_read_b128 v[60:63], v226
	ds_read_b128 v[64:67], v226 offset:4608
	ds_read_b128 v[68:71], v226 offset:32
	ds_read_b128 v[80:83], v226 offset:4640
	ds_read_b128 v[88:91], v226 offset:64
	ds_read_b128 v[92:95], v226 offset:4672
	ds_read_b128 v[96:99], v226 offset:96
	ds_read_b128 v[100:103], v226 offset:4704
	s_waitcnt lgkmcnt(6)
	v_mfma_f32_32x32x16_bf16 v[2:17], v[60:63], v[64:67], v[2:17]
	s_waitcnt lgkmcnt(4)
	v_mfma_f32_32x32x16_bf16 v[2:17], v[68:71], v[80:83], v[2:17]
	s_waitcnt lgkmcnt(2)
	v_mfma_f32_32x32x16_bf16 v[2:17], v[88:91], v[92:95], v[2:17]
	s_waitcnt lgkmcnt(0)
	v_mfma_f32_32x32x16_bf16 v[2:17], v[96:99], v[100:103], v[2:17]
	s_waitcnt vmcnt(24)
	ds_write_b128 v225, v[188:191]
	ds_write_b128 v225, v[192:195] offset:1152
	ds_write_b128 v225, v[196:199] offset:2304
	ds_write_b128 v225, v[200:203] offset:3456
	ds_write_b128 v225, v[204:207] offset:4608
	ds_write_b128 v225, v[208:211] offset:5760
	ds_write_b128 v225, v[212:215] offset:6912
	ds_write_b128 v225, v[216:219] offset:8064
	s_nop 1
	s_add_u32 s72, s66, 768
	s_addc_u32 s73, s67, 0
	s_add_u32 s74, s68, 768
	s_addc_u32 s75, s69, 0
	global_load_dwordx4 v[188:191], v224, s[72:73]
	global_load_dwordx4 v[204:207], v224, s[74:75]
	s_add_u32 s72, s66, 33536
	s_addc_u32 s73, s67, 0
	s_add_u32 s74, s68, 33536
	s_addc_u32 s75, s69, 0
	global_load_dwordx4 v[192:195], v224, s[72:73]
	global_load_dwordx4 v[208:211], v224, s[74:75]
	s_add_u32 s72, s66, 66304
	s_addc_u32 s73, s67, 0
	s_add_u32 s74, s68, 66304
	s_addc_u32 s75, s69, 0
	global_load_dwordx4 v[196:199], v224, s[72:73]
	global_load_dwordx4 v[212:215], v224, s[74:75]
	s_add_u32 s72, s66, 99072
	s_addc_u32 s73, s67, 0
	s_add_u32 s74, s68, 99072
	s_addc_u32 s75, s69, 0
	global_load_dwordx4 v[200:203], v224, s[72:73]
	global_load_dwordx4 v[216:219], v224, s[74:75]
	s_waitcnt lgkmcnt(0)
	ds_read_b128 v[60:63], v226
	ds_read_b128 v[64:67], v226 offset:4608
	ds_read_b128 v[68:71], v226 offset:32
	ds_read_b128 v[80:83], v226 offset:4640
	ds_read_b128 v[88:91], v226 offset:64
	ds_read_b128 v[92:95], v226 offset:4672
	ds_read_b128 v[96:99], v226 offset:96
	ds_read_b128 v[100:103], v226 offset:4704
	s_waitcnt lgkmcnt(6)
	v_mfma_f32_32x32x16_bf16 v[2:17], v[60:63], v[64:67], v[2:17]
	s_waitcnt lgkmcnt(4)
	v_mfma_f32_32x32x16_bf16 v[2:17], v[68:71], v[80:83], v[2:17]
	s_waitcnt lgkmcnt(2)
	v_mfma_f32_32x32x16_bf16 v[2:17], v[88:91], v[92:95], v[2:17]
	s_waitcnt lgkmcnt(0)
	v_mfma_f32_32x32x16_bf16 v[2:17], v[96:99], v[100:103], v[2:17]
	s_waitcnt vmcnt(24)
	ds_write_b128 v225, v[228:231]
	ds_write_b128 v225, v[232:235] offset:1152
	ds_write_b128 v225, v[236:239] offset:2304
	ds_write_b128 v225, v[240:243] offset:3456
	ds_write_b128 v225, v[244:247] offset:4608
	ds_write_b128 v225, v[248:251] offset:5760
	ds_write_b128 v225, v[52:55] offset:6912
	ds_write_b128 v225, v[56:59] offset:8064
	s_nop 1
	s_add_u32 s72, s66, 896
	s_addc_u32 s73, s67, 0
	s_add_u32 s74, s68, 896
	s_addc_u32 s75, s69, 0
	global_load_dwordx4 v[228:231], v224, s[72:73]
	global_load_dwordx4 v[244:247], v224, s[74:75]
	s_add_u32 s72, s66, 33664
	s_addc_u32 s73, s67, 0
	s_add_u32 s74, s68, 33664
	s_addc_u32 s75, s69, 0
	global_load_dwordx4 v[232:235], v224, s[72:73]
	global_load_dwordx4 v[248:251], v224, s[74:75]
	s_add_u32 s72, s66, 66432
	s_addc_u32 s73, s67, 0
	s_add_u32 s74, s68, 66432
	s_addc_u32 s75, s69, 0
	global_load_dwordx4 v[236:239], v224, s[72:73]
	global_load_dwordx4 v[52:55], v224, s[74:75]
	s_add_u32 s72, s66, 99200
	s_addc_u32 s73, s67, 0
	s_add_u32 s74, s68, 99200
	s_addc_u32 s75, s69, 0
	global_load_dwordx4 v[240:243], v224, s[72:73]
	global_load_dwordx4 v[56:59], v224, s[74:75]
	s_waitcnt lgkmcnt(0)
	ds_read_b128 v[60:63], v226
	ds_read_b128 v[64:67], v226 offset:4608
	ds_read_b128 v[68:71], v226 offset:32
	ds_read_b128 v[80:83], v226 offset:4640
	ds_read_b128 v[88:91], v226 offset:64
	ds_read_b128 v[92:95], v226 offset:4672
	ds_read_b128 v[96:99], v226 offset:96
	ds_read_b128 v[100:103], v226 offset:4704
	s_waitcnt lgkmcnt(6)
	v_mfma_f32_32x32x16_bf16 v[2:17], v[60:63], v[64:67], v[2:17]
	s_waitcnt lgkmcnt(4)
	v_mfma_f32_32x32x16_bf16 v[2:17], v[68:71], v[80:83], v[2:17]
	s_waitcnt lgkmcnt(2)
	v_mfma_f32_32x32x16_bf16 v[2:17], v[88:91], v[92:95], v[2:17]
	s_waitcnt lgkmcnt(0)
	v_mfma_f32_32x32x16_bf16 v[2:17], v[96:99], v[100:103], v[2:17]
	s_waitcnt vmcnt(24)
	ds_write_b128 v225, v[106:109]
	ds_write_b128 v225, v[110:113] offset:1152
	ds_write_b128 v225, v[114:117] offset:2304
	ds_write_b128 v225, v[118:121] offset:3456
	ds_write_b128 v225, v[122:125] offset:4608
	ds_write_b128 v225, v[126:129] offset:5760
	ds_write_b128 v225, v[130:133] offset:6912
	ds_write_b128 v225, v[134:137] offset:8064
	s_waitcnt lgkmcnt(0)
	ds_read_b128 v[60:63], v226
	ds_read_b128 v[64:67], v226 offset:4608
	ds_read_b128 v[68:71], v226 offset:32
	ds_read_b128 v[80:83], v226 offset:4640
	ds_read_b128 v[88:91], v226 offset:64
	ds_read_b128 v[92:95], v226 offset:4672
	ds_read_b128 v[96:99], v226 offset:96
	ds_read_b128 v[100:103], v226 offset:4704
	s_waitcnt lgkmcnt(6)
	v_mfma_f32_32x32x16_bf16 v[2:17], v[60:63], v[64:67], v[2:17]
	s_waitcnt lgkmcnt(4)
	v_mfma_f32_32x32x16_bf16 v[2:17], v[68:71], v[80:83], v[2:17]
	s_waitcnt lgkmcnt(2)
	v_mfma_f32_32x32x16_bf16 v[2:17], v[88:91], v[92:95], v[2:17]
	s_waitcnt lgkmcnt(0)
	v_mfma_f32_32x32x16_bf16 v[2:17], v[96:99], v[100:103], v[2:17]
	s_waitcnt vmcnt(16)
	ds_write_b128 v225, v[138:141]
	ds_write_b128 v225, v[142:145] offset:1152
	ds_write_b128 v225, v[146:149] offset:2304
	ds_write_b128 v225, v[168:171] offset:3456
	ds_write_b128 v225, v[172:175] offset:4608
	ds_write_b128 v225, v[176:179] offset:5760
	ds_write_b128 v225, v[180:183] offset:6912
	ds_write_b128 v225, v[184:187] offset:8064
	s_waitcnt lgkmcnt(0)
	ds_read_b128 v[60:63], v226
	ds_read_b128 v[64:67], v226 offset:4608
	ds_read_b128 v[68:71], v226 offset:32
	ds_read_b128 v[80:83], v226 offset:4640
	ds_read_b128 v[88:91], v226 offset:64
	ds_read_b128 v[92:95], v226 offset:4672
	ds_read_b128 v[96:99], v226 offset:96
	ds_read_b128 v[100:103], v226 offset:4704
	s_waitcnt lgkmcnt(6)
	v_mfma_f32_32x32x16_bf16 v[2:17], v[60:63], v[64:67], v[2:17]
	s_waitcnt lgkmcnt(4)
	v_mfma_f32_32x32x16_bf16 v[2:17], v[68:71], v[80:83], v[2:17]
	s_waitcnt lgkmcnt(2)
	v_mfma_f32_32x32x16_bf16 v[2:17], v[88:91], v[92:95], v[2:17]
	s_waitcnt lgkmcnt(0)
	v_mfma_f32_32x32x16_bf16 v[2:17], v[96:99], v[100:103], v[2:17]
	s_waitcnt vmcnt(8)
	ds_write_b128 v225, v[188:191]
	ds_write_b128 v225, v[192:195] offset:1152
	ds_write_b128 v225, v[196:199] offset:2304
	ds_write_b128 v225, v[200:203] offset:3456
	ds_write_b128 v225, v[204:207] offset:4608
	ds_write_b128 v225, v[208:211] offset:5760
	ds_write_b128 v225, v[212:215] offset:6912
	ds_write_b128 v225, v[216:219] offset:8064
	s_waitcnt lgkmcnt(0)
	ds_read_b128 v[60:63], v226
	ds_read_b128 v[64:67], v226 offset:4608
	ds_read_b128 v[68:71], v226 offset:32
	ds_read_b128 v[80:83], v226 offset:4640
	ds_read_b128 v[88:91], v226 offset:64
	ds_read_b128 v[92:95], v226 offset:4672
	ds_read_b128 v[96:99], v226 offset:96
	ds_read_b128 v[100:103], v226 offset:4704
	s_waitcnt lgkmcnt(6)
	v_mfma_f32_32x32x16_bf16 v[2:17], v[60:63], v[64:67], v[2:17]
	s_waitcnt lgkmcnt(4)
	v_mfma_f32_32x32x16_bf16 v[2:17], v[68:71], v[80:83], v[2:17]
	s_waitcnt lgkmcnt(2)
	v_mfma_f32_32x32x16_bf16 v[2:17], v[88:91], v[92:95], v[2:17]
	s_waitcnt lgkmcnt(0)
	v_mfma_f32_32x32x16_bf16 v[2:17], v[96:99], v[100:103], v[2:17]
	s_waitcnt vmcnt(0)
	ds_write_b128 v225, v[228:231]
	ds_write_b128 v225, v[232:235] offset:1152
	ds_write_b128 v225, v[236:239] offset:2304
	ds_write_b128 v225, v[240:243] offset:3456
	ds_write_b128 v225, v[244:247] offset:4608
	ds_write_b128 v225, v[248:251] offset:5760
	ds_write_b128 v225, v[52:55] offset:6912
	ds_write_b128 v225, v[56:59] offset:8064
	s_waitcnt lgkmcnt(0)
	ds_read_b128 v[60:63], v226
	ds_read_b128 v[64:67], v226 offset:4608
	ds_read_b128 v[68:71], v226 offset:32
	ds_read_b128 v[80:83], v226 offset:4640
	ds_read_b128 v[88:91], v226 offset:64
	ds_read_b128 v[92:95], v226 offset:4672
	ds_read_b128 v[96:99], v226 offset:96
	ds_read_b128 v[100:103], v226 offset:4704
	s_waitcnt lgkmcnt(6)
	v_mfma_f32_32x32x16_bf16 v[2:17], v[60:63], v[64:67], v[2:17]
	s_waitcnt lgkmcnt(4)
	v_mfma_f32_32x32x16_bf16 v[2:17], v[68:71], v[80:83], v[2:17]
	s_waitcnt lgkmcnt(2)
	v_mfma_f32_32x32x16_bf16 v[2:17], v[88:91], v[92:95], v[2:17]
	s_waitcnt lgkmcnt(0)
	v_mfma_f32_32x32x16_bf16 v[2:17], v[96:99], v[100:103], v[2:17]
.Lsk3_end_3:
	s_mov_b32 s22, 0x200
	s_mov_b32 s23, 0
	v_lshl_add_u64 v[54:55], v[20:21], 0, s[22:23]
	v_lshl_add_u64 v[56:57], v[28:29], 0, s[22:23]
	s_movk_i32 s14, 0x100
	s_mov_b64 s[16:17], 0
	s_mov_b64 vcc, exec
	s_nop 10
	ds_write2_b32 v32, v2, v3 offset1:33
	ds_write2_b32 v32, v4, v5 offset0:66 offset1:99
	v_add_u32_e32 v2, 0x400, v32
	ds_write2_b32 v2, v6, v7 offset0:8 offset1:41
	ds_write2_b32 v2, v8, v9 offset0:74 offset1:107
	v_add_u32_e32 v2, 0x800, v32
	ds_write2_b32 v2, v10, v11 offset0:16 offset1:49
	ds_write2_b32 v2, v12, v13 offset0:82 offset1:115
	v_add_u32_e32 v2, 0xc00, v32
	ds_write2_b32 v2, v14, v15 offset0:24 offset1:57
	ds_write2_b32 v2, v16, v17 offset0:90 offset1:123
	s_waitcnt lgkmcnt(0)
	s_barrier
	s_and_saveexec_b64 s[16:17], s[8:9]
	s_cbranch_execz .LBB0_1468
	s_and_b32 s14, s18, 0xe0
	v_or_b32_e32 v18, s14, v31
	s_and_b32 s18, s18, 0xffffff00
	v_or_b32_e32 v2, s18, v18
	s_ashr_i32 s19, s18, 31
	v_ashrrev_i32_e32 v3, 31, v2
	v_lshl_add_u64 v[6:7], v[24:25], 0, s[18:19]
	v_lshl_add_u64 v[28:29], v[2:3], 2, s[0:1]
	v_or_b32_e32 v6, v6, v18
	global_load_dwordx4 v[2:5], v[28:29], off
	v_lshlrev_b64 v[10:11], 1, v[6:7]
	v_lshl_add_u64 v[6:7], s[2:3], 0, v[10:11]
	global_load_dwordx4 v[6:9], v[6:7], off
	v_lshl_add_u64 v[34:35], s[10:11], 0, v[10:11]
	global_load_dwordx4 v[10:13], v[34:35], off
	global_load_dwordx4 v[14:17], v[28:29], off offset:16
	ds_read2_b32 v[28:29], v33 offset1:1
	ds_read2_b32 v[34:35], v33 offset0:2 offset1:3
	ds_read2_b32 v[36:37], v33 offset0:4 offset1:5
	ds_read2_b32 v[38:39], v33 offset0:6 offset1:7
	v_add_u32_e32 v40, 0x1080, v33
	v_add_u32_e32 v42, 0x2100, v33
	v_add_u32_e32 v44, 0x3180, v33
	v_add_u32_e32 v46, 0x1088, v33
	v_add_u32_e32 v48, 0x2108, v33
	v_add_u32_e32 v50, 0x3188, v33
	v_add_u32_e32 v52, 0x1090, v33
	v_add_u32_e32 v54, 0x2110, v33
	v_add_u32_e32 v56, 0x3190, v33
	v_add_u32_e32 v58, 0x1098, v33
	v_add_u32_e32 v60, 0x2118, v33
	v_add_u32_e32 v62, 0x3198, v33
	s_waitcnt lgkmcnt(3)
	v_add_f32_e32 v28, 0, v28
	v_add_f32_e32 v29, 0, v29
	ds_read2_b32 v[40:41], v40 offset1:1
	ds_read2_b32 v[42:43], v42 offset1:1
	ds_read2_b32 v[44:45], v44 offset1:1
	ds_read2_b32 v[46:47], v46 offset1:1
	ds_read2_b32 v[48:49], v48 offset1:1
	ds_read2_b32 v[50:51], v50 offset1:1
	ds_read2_b32 v[52:53], v52 offset1:1
	ds_read2_b32 v[54:55], v54 offset1:1
	ds_read2_b32 v[56:57], v56 offset1:1
	ds_read2_b32 v[58:59], v58 offset1:1
	ds_read2_b32 v[60:61], v60 offset1:1
	ds_read2_b32 v[62:63], v62 offset1:1
	s_waitcnt lgkmcnt(14)
	v_add_f32_e32 v34, 0, v34
	v_add_f32_e32 v35, 0, v35
	s_waitcnt lgkmcnt(11)
	v_add_f32_e32 v28, v28, v40
	v_add_f32_e32 v29, v29, v41
	s_waitcnt lgkmcnt(8)
	v_add_f32_e32 v34, v34, v46
	v_add_f32_e32 v35, v35, v47
	v_add_f32_e32 v28, v28, v42
	v_add_f32_e32 v29, v29, v43
	s_waitcnt lgkmcnt(7)
	v_add_f32_e32 v34, v34, v48
	v_add_f32_e32 v35, v35, v49
	v_add_f32_e32 v28, v28, v44
	v_add_f32_e32 v29, v29, v45
	s_waitcnt lgkmcnt(6)
	v_add_f32_e32 v34, v34, v50
	v_add_f32_e32 v35, v35, v51
	v_add_f32_e32 v36, 0, v36
	v_add_f32_e32 v37, 0, v37
	s_waitcnt lgkmcnt(5)
	v_add_f32_e32 v36, v36, v52
	v_add_f32_e32 v37, v37, v53
	s_waitcnt lgkmcnt(4)
	v_add_f32_e32 v36, v36, v54
	v_add_f32_e32 v37, v37, v55
	s_waitcnt lgkmcnt(3)
	v_add_f32_e32 v36, v36, v56
	v_add_f32_e32 v37, v37, v57
	v_add_f32_e32 v38, 0, v38
	v_add_f32_e32 v39, 0, v39
	s_waitcnt lgkmcnt(2)
	v_add_f32_e32 v38, v38, v58
	v_add_f32_e32 v39, v39, v59
	s_waitcnt lgkmcnt(1)
	v_add_f32_e32 v38, v38, v60
	v_add_f32_e32 v39, v39, v61
	s_waitcnt lgkmcnt(0)
	v_add_f32_e32 v38, v38, v62
	v_add_f32_e32 v39, v39, v63
	v_lshlrev_b32_e32 v18, 1, v18
	s_waitcnt vmcnt(3)
	v_add_f32_e32 v2, v28, v2
	v_add_f32_e32 v3, v29, v3
	v_add_f32_e32 v28, v34, v4
	v_add_f32_e32 v34, v35, v5
	v_mul_f32_e32 v5, 0xbfb8aa3b, v2
	v_mul_f32_e32 v29, 0xbfb8aa3b, v3
	s_waitcnt vmcnt(2)
	v_lshlrev_b32_e32 v2, 16, v6
	v_and_b32_e32 v3, 0xffff0000, v6
	v_exp_f32_e32 v6, v5
	v_exp_f32_e32 v29, v29
	s_waitcnt vmcnt(1)
	v_lshlrev_b32_e32 v4, 16, v10
	v_and_b32_e32 v5, 0xffff0000, v10
	v_add_f32_e32 v6, 1.0, v6
	v_add_f32_e32 v29, 1.0, v29
	v_mul_f32_e32 v10, 0xbfb8aa3b, v28
	v_rcp_f32_e32 v28, v6
	v_rcp_f32_e32 v29, v29
	v_mul_f32_e32 v6, 0xbfb8aa3b, v34
	v_exp_f32_e32 v10, v10
	v_exp_f32_e32 v6, v6
	v_pk_mul_f32 v[2:3], v[28:29], v[2:3]
	s_nop 0
	v_pk_mul_f32 v[2:3], v[2:3], v[4:5]
	v_add_f32_e32 v4, 1.0, v10
	v_add_f32_e32 v5, 1.0, v6
	v_rcp_f32_e32 v4, v4
	v_rcp_f32_e32 v5, v5
	v_lshlrev_b32_e32 v6, 16, v7
	v_and_b32_e32 v7, 0xffff0000, v7
	v_lshlrev_b32_e32 v10, 16, v11
	v_pk_mul_f32 v[4:5], v[4:5], v[6:7]
	s_waitcnt vmcnt(0)
	v_add_f32_e32 v6, v36, v14
	v_add_f32_e32 v7, v37, v15
	v_mul_f32_e32 v6, 0xbfb8aa3b, v6
	v_mul_f32_e32 v7, 0xbfb8aa3b, v7
	v_exp_f32_e32 v6, v6
	v_exp_f32_e32 v7, v7
	v_and_b32_e32 v11, 0xffff0000, v11
	v_pk_mul_f32 v[4:5], v[4:5], v[10:11]
	v_add_f32_e32 v6, 1.0, v6
	v_add_f32_e32 v7, 1.0, v7
	v_rcp_f32_e32 v6, v6
	v_rcp_f32_e32 v7, v7
	v_lshlrev_b32_e32 v10, 16, v8
	v_and_b32_e32 v11, 0xffff0000, v8
	v_add_f32_e32 v8, v38, v16
	v_pk_mul_f32 v[6:7], v[6:7], v[10:11]
	v_mul_f32_e32 v8, 0xbfb8aa3b, v8
	v_add_f32_e32 v10, v39, v17
	v_exp_f32_e32 v8, v8
	v_mul_f32_e32 v10, 0xbfb8aa3b, v10
	v_exp_f32_e32 v11, v10
	v_lshlrev_b32_e32 v14, 16, v12
	v_add_f32_e32 v8, 1.0, v8
	v_rcp_f32_e32 v10, v8
	v_add_f32_e32 v8, 1.0, v11
	v_rcp_f32_e32 v11, v8
	v_and_b32_e32 v15, 0xffff0000, v12
	v_lshlrev_b32_e32 v8, 16, v9
	v_and_b32_e32 v9, 0xffff0000, v9
	v_pk_mul_f32 v[6:7], v[6:7], v[14:15]
	v_lshlrev_b32_e32 v12, 16, v13
	v_and_b32_e32 v13, 0xffff0000, v13
	v_pk_mul_f32 v[8:9], v[10:11], v[8:9]
	v_cvt_pk_bf16_f32 v2, v2, v3
	v_pk_mul_f32 v[8:9], v[8:9], v[12:13]
	v_cvt_pk_bf16_f32 v3, v4, v5
	v_cvt_pk_bf16_f32 v4, v6, v7
	v_lshl_add_u64 v[6:7], s[18:19], 1, v[26:27]
	v_cvt_pk_bf16_f32 v5, v8, v9
	v_lshl_add_u64 v[6:7], v[6:7], 0, v[18:19]
	global_store_dwordx4 v[6:7], v[2:5], off
	s_branch .LBB0_1468

.LBB0_1668:
	s_and_b64 vcc, exec, s[0:1]
	s_cbranch_vccz .LBB0_1744
	s_cmp_lt_u32 s94, 64
	s_cselect_b64 s[50:51], -1, 0
	s_cselect_b64 s[6:7], 0, -1
	v_readlane_b32 s0, v255, 3
	v_readlane_b32 s1, v255, 4
	s_load_dwordx2 s[2:3], s[0:1], 0xd0
	s_load_dwordx4 s[12:15], s[0:1], 0xc0
	v_mov_b32_e32 v2, v0
	s_waitcnt lgkmcnt(0)
	s_add_u32 s16, s2, 0x7300000
	s_addc_u32 s17, s3, 0
	s_add_u32 s40, s2, 0x4a00000
	s_addc_u32 s41, s3, 0
	s_and_b64 vcc, exec, s[6:7]
	v_readfirstlane_b32 s0, v2
	s_cbranch_vccnz .LBB0_1677
	s_ashr_i32 s8, s0, 6
	s_ashr_i32 s0, s0, 3
	s_movk_i32 s1, 0xffe0
	v_mov_b32_e32 v4, s0
	v_bfi_b32 v4, s1, v4, v2
	v_ashrrev_i32_e32 v5, 31, v4
	v_lshlrev_b64 v[4:5], 12, v[4:5]
	s_lshl_b32 s0, s8, 10
	v_bfe_u32 v3, v2, 5, 1
	v_lshl_add_u64 v[4:5], s[2:3], 0, v[4:5]
	s_and_b32 s10, s0, 0xc00
	s_mov_b32 s11, 0
	v_lshl_add_u64 v[4:5], v[4:5], 0, s[10:11]
	v_lshlrev_b32_e32 v18, 4, v3
	v_mov_b32_e32 v19, 0
	v_lshl_add_u64 v[4:5], v[4:5], 0, v[18:19]
	s_mov_b64 s[0:1], 0xd500000
	v_lshl_add_u64 v[20:21], v[4:5], 0, s[0:1]
	s_add_u32 s0, s40, s10
	s_addc_u32 s1, s41, 0
	v_lshl_add_u64 v[22:23], s[0:1], 0, v[18:19]
	s_lshl_b32 s0, s8, 5
	v_lshl_or_b32 v8, v3, 2, s0
	s_movk_i32 s0, 0x100
	v_and_b32_e32 v32, 31, v2
	v_cmp_gt_i32_e64 s[0:1], s0, v2
	v_ashrrev_i32_e32 v4, 2, v2
	v_and_b32_e32 v5, 3, v2
	v_and_b32_e32 v2, 0x3fffff80, v2
	v_and_or_b32 v10, v4, 31, v2
	v_lshl_add_u32 v11, v5, 5, 0
	v_lshlrev_b32_e32 v33, 3, v5
	v_add_u32_e32 v2, 0x2000, v4
	v_cmp_eq_u32_e64 s[8:9], 0, v5
	v_ashrrev_i32_e32 v5, 31, v4
	v_ashrrev_i32_e32 v3, 31, v2
	v_lshl_add_u64 v[4:5], v[4:5], 2, s[2:3]
	s_mov_b64 s[18:19], 0x28000
	s_movk_i32 s10, 0x84
	v_lshl_add_u32 v9, v32, 2, 0
	v_lshlrev_b64 v[6:7], 12, v[2:3]
	v_lshlrev_b64 v[2:3], 13, v[2:3]
	v_lshl_add_u64 v[24:25], v[4:5], 0, s[18:19]
	v_mul_lo_u32 v4, v8, s10
	v_mul_lo_u32 v5, v10, s10
	v_lshl_add_u64 v[26:27], s[16:17], 0, v[6:7]
	v_lshl_add_u64 v[28:29], s[14:15], 0, v[2:3]
	v_add_u32_e32 v34, v9, v4
	v_add_u32_e32 v35, v11, v5
	v_mbcnt_hi_u32_b32 v36, -1, v1
	s_mov_b32 s22, s94
	s_branch .LBB0_1672

.LBB0_1672:
	s_lshl_b32 s20, s22, 5
	v_or_b32_e32 v2, s20, v32
	v_ashrrev_i32_e32 v3, 31, v2
	v_lshlrev_b64 v[2:3], 12, v[2:3]
	v_lshl_add_u64 v[30:31], v[22:23], 0, v[2:3]
	s_mov_b64 s[18:19], -1
	s_mov_b32 s10, s11
	v_mov_b32_e32 v2, 0
	v_mov_b32_e32 v3, v19
	v_mov_b32_e32 v4, v19
	v_mov_b32_e32 v5, v19
	v_mov_b32_e32 v6, v19
	v_mov_b32_e32 v7, v19
	v_mov_b32_e32 v8, v19
	v_mov_b32_e32 v9, v19
	v_mov_b32_e32 v10, v19
	v_mov_b32_e32 v11, v19
	v_mov_b32_e32 v12, v19
	v_mov_b32_e32 v13, v19
	v_mov_b32_e32 v14, v19
	v_mov_b32_e32 v15, v19
	v_mov_b32_e32 v16, v19
	v_mov_b32_e32 v17, v19
	v_readfirstlane_b32 s66, v20
	v_readfirstlane_b32 s67, v21
	v_readfirstlane_b32 s68, v30
	v_readfirstlane_b32 s69, v31
	v_readfirstlane_b32 s70, v0
	v_mbcnt_lo_u32_b32 v220, -1, 0
	v_mbcnt_hi_u32_b32 v220, -1, v220
	s_lshr_b32 s70, s70, 6
	s_mul_i32 s70, s70, 9216
	s_add_i32 s70, s70, 36864
	v_lshrrev_b32_e32 v221, 3, v220
	v_and_b32_e32 v222, 7, v220
	v_lshlrev_b32_e32 v224, 12, v221
	v_lshl_add_u32 v224, v222, 4, v224
	v_mul_u32_u24_e32 v225, 144, v221
	v_lshl_add_u32 v225, v222, 4, v225
	v_add_u32_e32 v225, s70, v225
	v_and_b32_e32 v221, 31, v220
	v_lshrrev_b32_e32 v222, 5, v220
	v_mul_u32_u24_e32 v226, 144, v221
	v_lshl_add_u32 v226, v222, 4, v226
	v_add_u32_e32 v226, s70, v226
	s_add_u32 s72, s66, 0
	s_addc_u32 s73, s67, 0
	s_add_u32 s74, s68, 0
	s_addc_u32 s75, s69, 0
	global_load_dwordx4 v[106:109], v224, s[72:73]
	global_load_dwordx4 v[122:125], v224, s[74:75]
	s_add_u32 s72, s66, 32768
	s_addc_u32 s73, s67, 0
	s_add_u32 s74, s68, 32768
	s_addc_u32 s75, s69, 0
	global_load_dwordx4 v[110:113], v224, s[72:73]
	global_load_dwordx4 v[126:129], v224, s[74:75]
	s_add_u32 s72, s66, 65536
	s_addc_u32 s73, s67, 0
	s_add_u32 s74, s68, 65536
	s_addc_u32 s75, s69, 0
	global_load_dwordx4 v[114:117], v224, s[72:73]
	global_load_dwordx4 v[130:133], v224, s[74:75]
	s_add_u32 s72, s66, 98304
	s_addc_u32 s73, s67, 0
	s_add_u32 s74, s68, 98304
	s_addc_u32 s75, s69, 0
	global_load_dwordx4 v[118:121], v224, s[72:73]
	global_load_dwordx4 v[134:137], v224, s[74:75]
	s_add_u32 s72, s66, 128
	s_addc_u32 s73, s67, 0
	s_add_u32 s74, s68, 128
	s_addc_u32 s75, s69, 0
	global_load_dwordx4 v[138:141], v224, s[72:73]
	global_load_dwordx4 v[172:175], v224, s[74:75]
	s_add_u32 s72, s66, 32896
	s_addc_u32 s73, s67, 0
	s_add_u32 s74, s68, 32896
	s_addc_u32 s75, s69, 0
	global_load_dwordx4 v[142:145], v224, s[72:73]
	global_load_dwordx4 v[176:179], v224, s[74:75]
	s_add_u32 s72, s66, 65664
	s_addc_u32 s73, s67, 0
	s_add_u32 s74, s68, 65664
	s_addc_u32 s75, s69, 0
	global_load_dwordx4 v[146:149], v224, s[72:73]
	global_load_dwordx4 v[180:183], v224, s[74:75]
	s_add_u32 s72, s66, 98432
	s_addc_u32 s73, s67, 0
	s_add_u32 s74, s68, 98432
	s_addc_u32 s75, s69, 0
	global_load_dwordx4 v[168:171], v224, s[72:73]
	global_load_dwordx4 v[184:187], v224, s[74:75]
	s_add_u32 s72, s66, 256
	s_addc_u32 s73, s67, 0
	s_add_u32 s74, s68, 256
	s_addc_u32 s75, s69, 0
	global_load_dwordx4 v[188:191], v224, s[72:73]
	global_load_dwordx4 v[204:207], v224, s[74:75]
	s_add_u32 s72, s66, 33024
	s_addc_u32 s73, s67, 0
	s_add_u32 s74, s68, 33024
	s_addc_u32 s75, s69, 0
	global_load_dwordx4 v[192:195], v224, s[72:73]
	global_load_dwordx4 v[208:211], v224, s[74:75]
	s_add_u32 s72, s66, 65792
	s_addc_u32 s73, s67, 0
	s_add_u32 s74, s68, 65792
	s_addc_u32 s75, s69, 0
	global_load_dwordx4 v[196:199], v224, s[72:73]
	global_load_dwordx4 v[212:215], v224, s[74:75]
	s_add_u32 s72, s66, 98560
	s_addc_u32 s73, s67, 0
	s_add_u32 s74, s68, 98560
	s_addc_u32 s75, s69, 0
	global_load_dwordx4 v[200:203], v224, s[72:73]
	global_load_dwordx4 v[216:219], v224, s[74:75]
	s_add_u32 s72, s66, 384
	s_addc_u32 s73, s67, 0
	s_add_u32 s74, s68, 384
	s_addc_u32 s75, s69, 0
	global_load_dwordx4 v[228:231], v224, s[72:73]
	global_load_dwordx4 v[244:247], v224, s[74:75]
	s_add_u32 s72, s66, 33152
	s_addc_u32 s73, s67, 0
	s_add_u32 s74, s68, 33152
	s_addc_u32 s75, s69, 0
	global_load_dwordx4 v[232:235], v224, s[72:73]
	global_load_dwordx4 v[248:251], v224, s[74:75]
	s_add_u32 s72, s66, 65920
	s_addc_u32 s73, s67, 0
	s_add_u32 s74, s68, 65920
	s_addc_u32 s75, s69, 0
	global_load_dwordx4 v[236:239], v224, s[72:73]
	global_load_dwordx4 v[52:55], v224, s[74:75]
	s_add_u32 s72, s66, 98688
	s_addc_u32 s73, s67, 0
	s_add_u32 s74, s68, 98688
	s_addc_u32 s75, s69, 0
	global_load_dwordx4 v[240:243], v224, s[72:73]
	global_load_dwordx4 v[56:59], v224, s[74:75]
	s_waitcnt vmcnt(24)
	ds_write_b128 v225, v[106:109]
	ds_write_b128 v225, v[110:113] offset:1152
	ds_write_b128 v225, v[114:117] offset:2304
	ds_write_b128 v225, v[118:121] offset:3456
	ds_write_b128 v225, v[122:125] offset:4608
	ds_write_b128 v225, v[126:129] offset:5760
	ds_write_b128 v225, v[130:133] offset:6912
	ds_write_b128 v225, v[134:137] offset:8064
	s_nop 1
	s_add_u32 s72, s66, 512
	s_addc_u32 s73, s67, 0
	s_add_u32 s74, s68, 512
	s_addc_u32 s75, s69, 0
	global_load_dwordx4 v[106:109], v224, s[72:73]
	global_load_dwordx4 v[122:125], v224, s[74:75]
	s_add_u32 s72, s66, 33280
	s_addc_u32 s73, s67, 0
	s_add_u32 s74, s68, 33280
	s_addc_u32 s75, s69, 0
	global_load_dwordx4 v[110:113], v224, s[72:73]
	global_load_dwordx4 v[126:129], v224, s[74:75]
	s_add_u32 s72, s66, 66048
	s_addc_u32 s73, s67, 0
	s_add_u32 s74, s68, 66048
	s_addc_u32 s75, s69, 0
	global_load_dwordx4 v[114:117], v224, s[72:73]
	global_load_dwordx4 v[130:133], v224, s[74:75]
	s_add_u32 s72, s66, 98816
	s_addc_u32 s73, s67, 0
	s_add_u32 s74, s68, 98816
	s_addc_u32 s75, s69, 0
	global_load_dwordx4 v[118:121], v224, s[72:73]
	global_load_dwordx4 v[134:137], v224, s[74:75]
	s_waitcnt lgkmcnt(0)
	ds_read_b128 v[60:63], v226
	ds_read_b128 v[64:67], v226 offset:4608
	ds_read_b128 v[68:71], v226 offset:32
	ds_read_b128 v[80:83], v226 offset:4640
	ds_read_b128 v[88:91], v226 offset:64
	ds_read_b128 v[92:95], v226 offset:4672
	ds_read_b128 v[96:99], v226 offset:96
	ds_read_b128 v[100:103], v226 offset:4704
	s_waitcnt lgkmcnt(6)
	v_mfma_f32_32x32x16_bf16 v[2:17], v[60:63], v[64:67], v[2:17]
	s_waitcnt lgkmcnt(4)
	v_mfma_f32_32x32x16_bf16 v[2:17], v[68:71], v[80:83], v[2:17]
	s_waitcnt lgkmcnt(2)
	v_mfma_f32_32x32x16_bf16 v[2:17], v[88:91], v[92:95], v[2:17]
	s_waitcnt lgkmcnt(0)
	v_mfma_f32_32x32x16_bf16 v[2:17], v[96:99], v[100:103], v[2:17]
	s_waitcnt vmcnt(24)
	ds_write_b128 v225, v[138:141]
	ds_write_b128 v225, v[142:145] offset:1152
	ds_write_b128 v225, v[146:149] offset:2304
	ds_write_b128 v225, v[168:171] offset:3456
	ds_write_b128 v225, v[172:175] offset:4608
	ds_write_b128 v225, v[176:179] offset:5760
	ds_write_b128 v225, v[180:183] offset:6912
	ds_write_b128 v225, v[184:187] offset:8064
	s_nop 1
	s_add_u32 s72, s66, 640
	s_addc_u32 s73, s67, 0
	s_add_u32 s74, s68, 640
	s_addc_u32 s75, s69, 0
	global_load_dwordx4 v[138:141], v224, s[72:73]
	global_load_dwordx4 v[172:175], v224, s[74:75]
	s_add_u32 s72, s66, 33408
	s_addc_u32 s73, s67, 0
	s_add_u32 s74, s68, 33408
	s_addc_u32 s75, s69, 0
	global_load_dwordx4 v[142:145], v224, s[72:73]
	global_load_dwordx4 v[176:179], v224, s[74:75]
	s_add_u32 s72, s66, 66176
	s_addc_u32 s73, s67, 0
	s_add_u32 s74, s68, 66176
	s_addc_u32 s75, s69, 0
	global_load_dwordx4 v[146:149], v224, s[72:73]
	global_load_dwordx4 v[180:183], v224, s[74:75]
	s_add_u32 s72, s66, 98944
	s_addc_u32 s73, s67, 0
	s_add_u32 s74, s68, 98944
	s_addc_u32 s75, s69, 0
	global_load_dwordx4 v[168:171], v224, s[72:73]
	global_load_dwordx4 v[184:187], v224, s[74:75]
	s_waitcnt lgkmcnt(0)
	ds_read_b128 v[60:63], v226
	ds_read_b128 v[64:67], v226 offset:4608
	ds_read_b128 v[68:71], v226 offset:32
	ds_read_b128 v[80:83], v226 offset:4640
	ds_read_b128 v[88:91], v226 offset:64
	ds_read_b128 v[92:95], v226 offset:4672
	ds_read_b128 v[96:99], v226 offset:96
	ds_read_b128 v[100:103], v226 offset:4704
	s_waitcnt lgkmcnt(6)
	v_mfma_f32_32x32x16_bf16 v[2:17], v[60:63], v[64:67], v[2:17]
	s_waitcnt lgkmcnt(4)
	v_mfma_f32_32x32x16_bf16 v[2:17], v[68:71], v[80:83], v[2:17]
	s_waitcnt lgkmcnt(2)
	v_mfma_f32_32x32x16_bf16 v[2:17], v[88:91], v[92:95], v[2:17]
	s_waitcnt lgkmcnt(0)
	v_mfma_f32_32x32x16_bf16 v[2:17], v[96:99], v[100:103], v[2:17]
	s_waitcnt vmcnt(24)
	ds_write_b128 v225, v[188:191]
	ds_write_b128 v225, v[192:195] offset:1152
	ds_write_b128 v225, v[196:199] offset:2304
	ds_write_b128 v225, v[200:203] offset:3456
	ds_write_b128 v225, v[204:207] offset:4608
	ds_write_b128 v225, v[208:211] offset:5760
	ds_write_b128 v225, v[212:215] offset:6912
	ds_write_b128 v225, v[216:219] offset:8064
	s_nop 1
	s_add_u32 s72, s66, 768
	s_addc_u32 s73, s67, 0
	s_add_u32 s74, s68, 768
	s_addc_u32 s75, s69, 0
	global_load_dwordx4 v[188:191], v224, s[72:73]
	global_load_dwordx4 v[204:207], v224, s[74:75]
	s_add_u32 s72, s66, 33536
	s_addc_u32 s73, s67, 0
	s_add_u32 s74, s68, 33536
	s_addc_u32 s75, s69, 0
	global_load_dwordx4 v[192:195], v224, s[72:73]
	global_load_dwordx4 v[208:211], v224, s[74:75]
	s_add_u32 s72, s66, 66304
	s_addc_u32 s73, s67, 0
	s_add_u32 s74, s68, 66304
	s_addc_u32 s75, s69, 0
	global_load_dwordx4 v[196:199], v224, s[72:73]
	global_load_dwordx4 v[212:215], v224, s[74:75]
	s_add_u32 s72, s66, 99072
	s_addc_u32 s73, s67, 0
	s_add_u32 s74, s68, 99072
	s_addc_u32 s75, s69, 0
	global_load_dwordx4 v[200:203], v224, s[72:73]
	global_load_dwordx4 v[216:219], v224, s[74:75]
	s_waitcnt lgkmcnt(0)
	ds_read_b128 v[60:63], v226
	ds_read_b128 v[64:67], v226 offset:4608
	ds_read_b128 v[68:71], v226 offset:32
	ds_read_b128 v[80:83], v226 offset:4640
	ds_read_b128 v[88:91], v226 offset:64
	ds_read_b128 v[92:95], v226 offset:4672
	ds_read_b128 v[96:99], v226 offset:96
	ds_read_b128 v[100:103], v226 offset:4704
	s_waitcnt lgkmcnt(6)
	v_mfma_f32_32x32x16_bf16 v[2:17], v[60:63], v[64:67], v[2:17]
	s_waitcnt lgkmcnt(4)
	v_mfma_f32_32x32x16_bf16 v[2:17], v[68:71], v[80:83], v[2:17]
	s_waitcnt lgkmcnt(2)
	v_mfma_f32_32x32x16_bf16 v[2:17], v[88:91], v[92:95], v[2:17]
	s_waitcnt lgkmcnt(0)
	v_mfma_f32_32x32x16_bf16 v[2:17], v[96:99], v[100:103], v[2:17]
	s_waitcnt vmcnt(24)
	ds_write_b128 v225, v[228:231]
	ds_write_b128 v225, v[232:235] offset:1152
	ds_write_b128 v225, v[236:239] offset:2304
	ds_write_b128 v225, v[240:243] offset:3456
	ds_write_b128 v225, v[244:247] offset:4608
	ds_write_b128 v225, v[248:251] offset:5760
	ds_write_b128 v225, v[52:55] offset:6912
	ds_write_b128 v225, v[56:59] offset:8064
	s_nop 1
	s_add_u32 s72, s66, 896
	s_addc_u32 s73, s67, 0
	s_add_u32 s74, s68, 896
	s_addc_u32 s75, s69, 0
	global_load_dwordx4 v[228:231], v224, s[72:73]
	global_load_dwordx4 v[244:247], v224, s[74:75]
	s_add_u32 s72, s66, 33664
	s_addc_u32 s73, s67, 0
	s_add_u32 s74, s68, 33664
	s_addc_u32 s75, s69, 0
	global_load_dwordx4 v[232:235], v224, s[72:73]
	global_load_dwordx4 v[248:251], v224, s[74:75]
	s_add_u32 s72, s66, 66432
	s_addc_u32 s73, s67, 0
	s_add_u32 s74, s68, 66432
	s_addc_u32 s75, s69, 0
	global_load_dwordx4 v[236:239], v224, s[72:73]
	global_load_dwordx4 v[52:55], v224, s[74:75]
	s_add_u32 s72, s66, 99200
	s_addc_u32 s73, s67, 0
	s_add_u32 s74, s68, 99200
	s_addc_u32 s75, s69, 0
	global_load_dwordx4 v[240:243], v224, s[72:73]
	global_load_dwordx4 v[56:59], v224, s[74:75]
	s_waitcnt lgkmcnt(0)
	ds_read_b128 v[60:63], v226
	ds_read_b128 v[64:67], v226 offset:4608
	ds_read_b128 v[68:71], v226 offset:32
	ds_read_b128 v[80:83], v226 offset:4640
	ds_read_b128 v[88:91], v226 offset:64
	ds_read_b128 v[92:95], v226 offset:4672
	ds_read_b128 v[96:99], v226 offset:96
	ds_read_b128 v[100:103], v226 offset:4704
	s_waitcnt lgkmcnt(6)
	v_mfma_f32_32x32x16_bf16 v[2:17], v[60:63], v[64:67], v[2:17]
	s_waitcnt lgkmcnt(4)
	v_mfma_f32_32x32x16_bf16 v[2:17], v[68:71], v[80:83], v[2:17]
	s_waitcnt lgkmcnt(2)
	v_mfma_f32_32x32x16_bf16 v[2:17], v[88:91], v[92:95], v[2:17]
	s_waitcnt lgkmcnt(0)
	v_mfma_f32_32x32x16_bf16 v[2:17], v[96:99], v[100:103], v[2:17]
	s_waitcnt vmcnt(24)
	ds_write_b128 v225, v[106:109]
	ds_write_b128 v225, v[110:113] offset:1152
	ds_write_b128 v225, v[114:117] offset:2304
	ds_write_b128 v225, v[118:121] offset:3456
	ds_write_b128 v225, v[122:125] offset:4608
	ds_write_b128 v225, v[126:129] offset:5760
	ds_write_b128 v225, v[130:133] offset:6912
	ds_write_b128 v225, v[134:137] offset:8064
	s_waitcnt lgkmcnt(0)
	ds_read_b128 v[60:63], v226
	ds_read_b128 v[64:67], v226 offset:4608
	ds_read_b128 v[68:71], v226 offset:32
	ds_read_b128 v[80:83], v226 offset:4640
	ds_read_b128 v[88:91], v226 offset:64
	ds_read_b128 v[92:95], v226 offset:4672
	ds_read_b128 v[96:99], v226 offset:96
	ds_read_b128 v[100:103], v226 offset:4704
	s_waitcnt lgkmcnt(6)
	v_mfma_f32_32x32x16_bf16 v[2:17], v[60:63], v[64:67], v[2:17]
	s_waitcnt lgkmcnt(4)
	v_mfma_f32_32x32x16_bf16 v[2:17], v[68:71], v[80:83], v[2:17]
	s_waitcnt lgkmcnt(2)
	v_mfma_f32_32x32x16_bf16 v[2:17], v[88:91], v[92:95], v[2:17]
	s_waitcnt lgkmcnt(0)
	v_mfma_f32_32x32x16_bf16 v[2:17], v[96:99], v[100:103], v[2:17]
	s_waitcnt vmcnt(16)
	ds_write_b128 v225, v[138:141]
	ds_write_b128 v225, v[142:145] offset:1152
	ds_write_b128 v225, v[146:149] offset:2304
	ds_write_b128 v225, v[168:171] offset:3456
	ds_write_b128 v225, v[172:175] offset:4608
	ds_write_b128 v225, v[176:179] offset:5760
	ds_write_b128 v225, v[180:183] offset:6912
	ds_write_b128 v225, v[184:187] offset:8064
	s_waitcnt lgkmcnt(0)
	ds_read_b128 v[60:63], v226
	ds_read_b128 v[64:67], v226 offset:4608
	ds_read_b128 v[68:71], v226 offset:32
	ds_read_b128 v[80:83], v226 offset:4640
	ds_read_b128 v[88:91], v226 offset:64
	ds_read_b128 v[92:95], v226 offset:4672
	ds_read_b128 v[96:99], v226 offset:96
	ds_read_b128 v[100:103], v226 offset:4704
	s_waitcnt lgkmcnt(6)
	v_mfma_f32_32x32x16_bf16 v[2:17], v[60:63], v[64:67], v[2:17]
	s_waitcnt lgkmcnt(4)
	v_mfma_f32_32x32x16_bf16 v[2:17], v[68:71], v[80:83], v[2:17]
	s_waitcnt lgkmcnt(2)
	v_mfma_f32_32x32x16_bf16 v[2:17], v[88:91], v[92:95], v[2:17]
	s_waitcnt lgkmcnt(0)
	v_mfma_f32_32x32x16_bf16 v[2:17], v[96:99], v[100:103], v[2:17]
	s_waitcnt vmcnt(8)
	ds_write_b128 v225, v[188:191]
	ds_write_b128 v225, v[192:195] offset:1152
	ds_write_b128 v225, v[196:199] offset:2304
	ds_write_b128 v225, v[200:203] offset:3456
	ds_write_b128 v225, v[204:207] offset:4608
	ds_write_b128 v225, v[208:211] offset:5760
	ds_write_b128 v225, v[212:215] offset:6912
	ds_write_b128 v225, v[216:219] offset:8064
	s_waitcnt lgkmcnt(0)
	ds_read_b128 v[60:63], v226
	ds_read_b128 v[64:67], v226 offset:4608
	ds_read_b128 v[68:71], v226 offset:32
	ds_read_b128 v[80:83], v226 offset:4640
	ds_read_b128 v[88:91], v226 offset:64
	ds_read_b128 v[92:95], v226 offset:4672
	ds_read_b128 v[96:99], v226 offset:96
	ds_read_b128 v[100:103], v226 offset:4704
	s_waitcnt lgkmcnt(6)
	v_mfma_f32_32x32x16_bf16 v[2:17], v[60:63], v[64:67], v[2:17]
	s_waitcnt lgkmcnt(4)
	v_mfma_f32_32x32x16_bf16 v[2:17], v[68:71], v[80:83], v[2:17]
	s_waitcnt lgkmcnt(2)
	v_mfma_f32_32x32x16_bf16 v[2:17], v[88:91], v[92:95], v[2:17]
	s_waitcnt lgkmcnt(0)
	v_mfma_f32_32x32x16_bf16 v[2:17], v[96:99], v[100:103], v[2:17]
	s_waitcnt vmcnt(0)
	ds_write_b128 v225, v[228:231]
	ds_write_b128 v225, v[232:235] offset:1152
	ds_write_b128 v225, v[236:239] offset:2304
	ds_write_b128 v225, v[240:243] offset:3456
	ds_write_b128 v225, v[244:247] offset:4608
	ds_write_b128 v225, v[248:251] offset:5760
	ds_write_b128 v225, v[52:55] offset:6912
	ds_write_b128 v225, v[56:59] offset:8064
	s_waitcnt lgkmcnt(0)
	ds_read_b128 v[60:63], v226
	ds_read_b128 v[64:67], v226 offset:4608
	ds_read_b128 v[68:71], v226 offset:32
	ds_read_b128 v[80:83], v226 offset:4640
	ds_read_b128 v[88:91], v226 offset:64
	ds_read_b128 v[92:95], v226 offset:4672
	ds_read_b128 v[96:99], v226 offset:96
	ds_read_b128 v[100:103], v226 offset:4704
	s_waitcnt lgkmcnt(6)
	v_mfma_f32_32x32x16_bf16 v[2:17], v[60:63], v[64:67], v[2:17]
	s_waitcnt lgkmcnt(4)
	v_mfma_f32_32x32x16_bf16 v[2:17], v[68:71], v[80:83], v[2:17]
	s_waitcnt lgkmcnt(2)
	v_mfma_f32_32x32x16_bf16 v[2:17], v[88:91], v[92:95], v[2:17]
	s_waitcnt lgkmcnt(0)
	v_mfma_f32_32x32x16_bf16 v[2:17], v[96:99], v[100:103], v[2:17]
	s_mov_b32 s24, 0x200
	s_mov_b32 s25, 0
	v_lshl_add_u64 v[58:59], v[20:21], 0, s[24:25]
	v_lshl_add_u64 v[60:61], v[30:31], 0, s[24:25]
	s_movk_i32 s10, 0x100
	s_mov_b64 s[18:19], 0
	s_mov_b64 vcc, exec
	s_nop 10
	ds_write2_b32 v34, v2, v3 offset1:33
	ds_write2_b32 v34, v4, v5 offset0:66 offset1:99
	v_add_u32_e32 v2, 0x400, v34
	ds_write2_b32 v2, v6, v7 offset0:8 offset1:41
	ds_write2_b32 v2, v8, v9 offset0:74 offset1:107
	v_add_u32_e32 v2, 0x800, v34
	ds_write2_b32 v2, v10, v11 offset0:16 offset1:49
	ds_write2_b32 v2, v12, v13 offset0:82 offset1:115
	v_add_u32_e32 v2, 0xc00, v34
	ds_write2_b32 v2, v14, v15 offset0:24 offset1:57
	ds_write2_b32 v2, v16, v17 offset0:90 offset1:123
	s_waitcnt lgkmcnt(0)
	s_barrier
	s_and_saveexec_b64 s[18:19], s[0:1]
	s_cbranch_execz .LBB0_1671
	s_and_b32 s10, s20, 0xe0
	s_and_b32 s20, s20, 0xffffff00
	v_or_b32_e32 v37, s10, v33
	s_ashr_i32 s21, s20, 31
	v_lshl_add_u64 v[2:3], s[20:21], 1, v[26:27]
	v_lshlrev_b32_e32 v18, 1, v37
	v_lshl_add_u64 v[2:3], v[2:3], 0, v[18:19]
	global_load_dwordx4 v[2:5], v[2:3], off
	ds_read2_b32 v[6:7], v35 offset1:1
	ds_read2_b32 v[8:9], v35 offset0:2 offset1:3
	ds_read2_b32 v[10:11], v35 offset0:4 offset1:5
	ds_read2_b32 v[12:13], v35 offset0:6 offset1:7
	v_add_u32_e32 v14, 0x1080, v35
	v_add_u32_e32 v16, 0x2100, v35
	v_add_u32_e32 v38, 0x1088, v35
	v_add_u32_e32 v40, 0x2108, v35
	v_add_u32_e32 v42, 0x3188, v35
	v_add_u32_e32 v44, 0x1090, v35
	v_add_u32_e32 v46, 0x2110, v35
	v_add_u32_e32 v48, 0x3190, v35
	v_add_u32_e32 v50, 0x1098, v35
	v_add_u32_e32 v52, 0x2118, v35
	v_add_u32_e32 v54, 0x3198, v35
	v_add_u32_e32 v18, 0x3180, v35
	ds_read2_b32 v[14:15], v14 offset1:1
	ds_read2_b32 v[16:17], v16 offset1:1
	ds_read2_b32 v[30:31], v18 offset1:1
	ds_read2_b32 v[38:39], v38 offset1:1
	ds_read2_b32 v[40:41], v40 offset1:1
	ds_read2_b32 v[42:43], v42 offset1:1
	ds_read2_b32 v[44:45], v44 offset1:1
	ds_read2_b32 v[46:47], v46 offset1:1
	ds_read2_b32 v[48:49], v48 offset1:1
	ds_read2_b32 v[50:51], v50 offset1:1
	ds_read2_b32 v[52:53], v52 offset1:1
	ds_read2_b32 v[54:55], v54 offset1:1
	s_waitcnt lgkmcnt(14)
	v_pk_add_f32 v[6:7], v[6:7], 0 op_sel_hi:[1,0]
	v_pk_add_f32 v[8:9], v[8:9], 0 op_sel_hi:[1,0]
	s_waitcnt lgkmcnt(11)
	v_pk_add_f32 v[6:7], v[6:7], v[14:15]
	v_pk_add_f32 v[10:11], v[10:11], 0 op_sel_hi:[1,0]
	v_pk_add_f32 v[12:13], v[12:13], 0 op_sel_hi:[1,0]
	s_waitcnt lgkmcnt(8)
	v_pk_add_f32 v[8:9], v[8:9], v[38:39]
	v_pk_add_f32 v[6:7], v[6:7], v[16:17]
	s_waitcnt lgkmcnt(5)
	v_pk_add_f32 v[10:11], v[10:11], v[44:45]
	s_waitcnt lgkmcnt(2)
	v_pk_add_f32 v[12:13], v[12:13], v[50:51]
	v_pk_add_f32 v[8:9], v[8:9], v[40:41]
	v_pk_add_f32 v[6:7], v[6:7], v[30:31]
	v_pk_add_f32 v[10:11], v[10:11], v[46:47]
	s_waitcnt lgkmcnt(1)
	v_pk_add_f32 v[12:13], v[12:13], v[52:53]
	v_pk_add_f32 v[8:9], v[8:9], v[42:43]
	v_pk_add_f32 v[10:11], v[10:11], v[48:49]
	s_waitcnt lgkmcnt(0)
	v_pk_add_f32 v[12:13], v[12:13], v[54:55]
	v_and_b32_e32 v57, 64, v36
	v_xor_b32_e32 v56, 1, v36
	v_add_u32_e32 v18, 64, v57
	v_cmp_lt_i32_e32 vcc, v56, v18
	s_waitcnt vmcnt(0)
	v_lshlrev_b32_e32 v14, 16, v2
	v_and_b32_e32 v15, 0xffff0000, v2
	v_lshlrev_b32_e32 v2, 16, v3
	v_and_b32_e32 v3, 0xffff0000, v3
	v_lshlrev_b32_e32 v16, 16, v4
	v_and_b32_e32 v17, 0xffff0000, v4
	v_lshlrev_b32_e32 v30, 16, v5
	v_and_b32_e32 v31, 0xffff0000, v5
	v_pk_add_f32 v[4:5], v[6:7], v[14:15]
	v_pk_add_f32 v[6:7], v[8:9], v[2:3]
	v_pk_mul_f32 v[2:3], v[4:5], v[4:5]
	v_pk_add_f32 v[8:9], v[10:11], v[16:17]
	v_pk_add_f32 v[10:11], v[12:13], v[30:31]
	v_pk_mul_f32 v[12:13], v[6:7], v[6:7]
	v_add_f32_e32 v2, v2, v3
	v_add_f32_e32 v2, v12, v2
	v_pk_mul_f32 v[14:15], v[8:9], v[8:9]
	v_add_f32_e32 v2, v13, v2
	v_add_f32_e32 v2, v14, v2
	v_pk_mul_f32 v[16:17], v[10:11], v[10:11]
	v_add_f32_e32 v2, v15, v2
	v_cndmask_b32_e32 v56, v36, v56, vcc
	v_add_f32_e32 v2, v16, v2
	v_lshlrev_b32_e32 v56, 2, v56
	v_add_f32_e32 v2, v17, v2
	ds_bpermute_b32 v3, v56, v2
	v_xor_b32_e32 v14, 2, v36
	v_cmp_lt_i32_e32 vcc, v14, v18
	v_lshl_add_u64 v[12:13], s[20:21], 2, v[28:29]
	v_lshlrev_b32_e32 v18, 2, v37
	v_cndmask_b32_e32 v14, v36, v14, vcc
	s_waitcnt lgkmcnt(0)
	v_add_f32_e32 v2, v2, v3
	v_lshlrev_b32_e32 v3, 2, v14
	ds_bpermute_b32 v3, v3, v2
	v_lshl_add_u64 v[12:13], v[12:13], 0, v[18:19]
	global_store_dwordx4 v[12:13], v[4:7], off
	global_store_dwordx4 v[12:13], v[8:11], off offset:16
	s_and_b64 exec, exec, s[8:9]
	s_cbranch_execz .LBB0_1671
	s_waitcnt lgkmcnt(0)
	v_add_f32_e32 v2, v2, v3
	global_atomic_add_f32 v[24:25], v2, off
	s_branch .LBB0_1671
